# scan stepper: S.n and S.r dot products as one packed fma chain each (one packed op less per dot product, reassociated f32 sum)
# speedup vs baseline: 1.0118x; 1.0054x over previous
.LBB0_639:
	s_and_b32 s20, s95, 1
	s_and_saveexec_b64 s[4:5], s[8:9]
	s_xor_b64 s[18:19], exec, s[4:5]
	s_cbranch_execz .LBB0_641
	s_setprio 3
	s_mul_i32 s4, s20, 0xb400
	s_add_i32 s4, s4, 0
	v_add_u32_e32 v2, s4, v108
	v_lshl_add_u32 v104, v48, 2, s4
	v_lshl_add_u32 v105, s20, 12, v117
	ds_read_b128 v[134:137], v2 offset:256
	ds_read_b128 v[138:141], v2 offset:272
	ds_read_b128 v[142:145], v2 offset:512
	ds_read_b128 v[146:149], v2 offset:528
	ds_read_b128 v[150:153], v2 offset:768
	ds_read_b128 v[154:157], v2 offset:784
	ds_read_b32 v210, v104 offset:1280
	ds_read_b128 v[126:129], v2 offset:0
	ds_read_b128 v[130:133], v2 offset:16
	ds_read_b128 v[158:161], v2 offset:1024
	ds_read_b128 v[162:165], v2 offset:1040
	s_waitcnt lgkmcnt(9)
	v_pk_mul_f32 v[134:135], v[96:97], v[134:135]
	s_nop 0
	v_pk_fma_f32 v[134:135], v[98:99], v[136:137], v[134:135]
	s_nop 0
	v_pk_fma_f32 v[134:135], v[100:101], v[138:139], v[134:135]
	s_nop 0
	v_pk_fma_f32 v[134:135], v[102:103], v[140:141], v[134:135]
	s_nop 0
	v_add_f32_e32 v136, v134, v135
	ds_read_b128 v[174:177], v2 offset:1696
	s_nop 0
	v_add_f32_dpp v136, v136, v136 quad_perm:[1,0,3,2] row_mask:0xf bank_mask:0xf bound_ctrl:1
	ds_read_b128 v[178:181], v2 offset:1712
	ds_read_b128 v[182:185], v2 offset:1952
	v_add_f32_dpp v136, v136, v136 quad_perm:[2,3,0,1] row_mask:0xf bank_mask:0xf bound_ctrl:1
	ds_read_b128 v[186:189], v2 offset:1968
	ds_read_b128 v[192:195], v2 offset:2208
	v_add_f32_dpp v136, v136, v136 row_half_mirror row_mask:0xf bank_mask:0xf bound_ctrl:1
	s_waitcnt lgkmcnt(12)
	v_pk_mul_f32 v[142:143], v[142:143], v[136:137] op_sel_hi:[1,0]
	v_pk_mul_f32 v[144:145], v[144:145], v[136:137] op_sel_hi:[1,0]
	v_pk_mul_f32 v[146:147], v[146:147], v[136:137] op_sel_hi:[1,0]
	v_pk_mul_f32 v[148:149], v[148:149], v[136:137] op_sel_hi:[1,0]
	ds_read_b128 v[196:199], v2 offset:2224
	s_waitcnt lgkmcnt(10)
	v_pk_fma_f32 v[142:143], v[150:151], v[210:211], v[142:143] op_sel_hi:[1,0,1]
	v_pk_fma_f32 v[144:145], v[152:153], v[210:211], v[144:145] op_sel_hi:[1,0,1]
	v_pk_fma_f32 v[146:147], v[154:155], v[210:211], v[146:147] op_sel_hi:[1,0,1]
	v_pk_fma_f32 v[148:149], v[156:157], v[210:211], v[148:149] op_sel_hi:[1,0,1]
	ds_read_b32 v212, v104 offset:2720
	ds_read_b128 v[166:169], v2 offset:1440
	s_waitcnt lgkmcnt(10)
	v_pk_fma_f32 v[96:97], v[96:97], v[126:127], v[142:143]
	v_pk_fma_f32 v[98:99], v[98:99], v[128:129], v[144:145]
	v_pk_fma_f32 v[100:101], v[100:101], v[130:131], v[146:147]
	v_pk_fma_f32 v[102:103], v[102:103], v[132:133], v[148:149]
	ds_read_b128 v[170:173], v2 offset:1456
	ds_read_b128 v[200:203], v2 offset:2464
	ds_read_b128 v[204:207], v2 offset:2480
	s_waitcnt lgkmcnt(9)
	v_pk_mul_f32 v[174:175], v[96:97], v[174:175]
	v_pk_mul_f32 v[158:159], v[96:97], v[158:159]
	v_pk_fma_f32 v[174:175], v[98:99], v[176:177], v[174:175]
	v_pk_fma_f32 v[158:159], v[98:99], v[160:161], v[158:159]
	v_pk_fma_f32 v[174:175], v[100:101], v[178:179], v[174:175]
	v_pk_fma_f32 v[158:159], v[100:101], v[162:163], v[158:159]
	v_pk_fma_f32 v[174:175], v[102:103], v[180:181], v[174:175]
	v_pk_fma_f32 v[158:159], v[102:103], v[164:165], v[158:159]
	v_add_f32_e32 v176, v174, v175
	v_add_f32_e32 v211, v158, v159
	ds_read_b128 v[134:137], v2 offset:3136
	v_add_f32_dpp v176, v176, v176 quad_perm:[1,0,3,2] row_mask:0xf bank_mask:0xf bound_ctrl:1
	ds_read_b128 v[138:141], v2 offset:3152
	ds_read_b128 v[142:145], v2 offset:3392
	v_add_f32_dpp v176, v176, v176 quad_perm:[2,3,0,1] row_mask:0xf bank_mask:0xf bound_ctrl:1
	ds_read_b128 v[146:149], v2 offset:3408
	ds_read_b128 v[150:153], v2 offset:3648
	v_add_f32_dpp v176, v176, v176 row_half_mirror row_mask:0xf bank_mask:0xf bound_ctrl:1
	s_waitcnt lgkmcnt(12)
	v_pk_mul_f32 v[182:183], v[182:183], v[176:177] op_sel_hi:[1,0]
	v_pk_mul_f32 v[184:185], v[184:185], v[176:177] op_sel_hi:[1,0]
	v_pk_mul_f32 v[186:187], v[186:187], v[176:177] op_sel_hi:[1,0]
	v_pk_mul_f32 v[188:189], v[188:189], v[176:177] op_sel_hi:[1,0]
	ds_read_b128 v[154:157], v2 offset:3664
	s_waitcnt lgkmcnt(10)
	v_pk_fma_f32 v[182:183], v[192:193], v[212:213], v[182:183] op_sel_hi:[1,0,1]
	v_pk_fma_f32 v[184:185], v[194:195], v[212:213], v[184:185] op_sel_hi:[1,0,1]
	v_pk_fma_f32 v[186:187], v[196:197], v[212:213], v[186:187] op_sel_hi:[1,0,1]
	v_pk_fma_f32 v[188:189], v[198:199], v[212:213], v[188:189] op_sel_hi:[1,0,1]
	ds_read_b32 v210, v104 offset:4160
	ds_read_b128 v[126:129], v2 offset:2880
	s_waitcnt lgkmcnt(10)
	v_pk_fma_f32 v[96:97], v[96:97], v[166:167], v[182:183]
	v_pk_fma_f32 v[98:99], v[98:99], v[168:169], v[184:185]
	v_pk_fma_f32 v[100:101], v[100:101], v[170:171], v[186:187]
	v_pk_fma_f32 v[102:103], v[102:103], v[172:173], v[188:189]
	ds_read_b128 v[130:133], v2 offset:2896
	ds_read_b128 v[158:161], v2 offset:3904
	ds_read_b128 v[162:165], v2 offset:3920
	s_waitcnt lgkmcnt(9)
	v_pk_mul_f32 v[134:135], v[96:97], v[134:135]
	v_pk_mul_f32 v[200:201], v[96:97], v[200:201]
	v_pk_fma_f32 v[134:135], v[98:99], v[136:137], v[134:135]
	v_pk_fma_f32 v[200:201], v[98:99], v[202:203], v[200:201]
	v_pk_fma_f32 v[134:135], v[100:101], v[138:139], v[134:135]
	v_pk_fma_f32 v[200:201], v[100:101], v[204:205], v[200:201]
	v_pk_fma_f32 v[134:135], v[102:103], v[140:141], v[134:135]
	v_pk_fma_f32 v[200:201], v[102:103], v[206:207], v[200:201]
	v_add_f32_e32 v136, v134, v135
	v_add_f32_e32 v213, v200, v201
	ds_read_b128 v[174:177], v2 offset:4576
	v_add_f32_dpp v136, v136, v136 quad_perm:[1,0,3,2] row_mask:0xf bank_mask:0xf bound_ctrl:1
	ds_read_b128 v[178:181], v2 offset:4592
	ds_read_b128 v[182:185], v2 offset:4832
	v_add_f32_dpp v136, v136, v136 quad_perm:[2,3,0,1] row_mask:0xf bank_mask:0xf bound_ctrl:1
	ds_read_b128 v[186:189], v2 offset:4848
	ds_read_b128 v[192:195], v2 offset:5088
	v_add_f32_dpp v136, v136, v136 row_half_mirror row_mask:0xf bank_mask:0xf bound_ctrl:1
	s_waitcnt lgkmcnt(12)
	v_pk_mul_f32 v[142:143], v[142:143], v[136:137] op_sel_hi:[1,0]
	v_pk_mul_f32 v[144:145], v[144:145], v[136:137] op_sel_hi:[1,0]
	v_pk_mul_f32 v[146:147], v[146:147], v[136:137] op_sel_hi:[1,0]
	v_pk_mul_f32 v[148:149], v[148:149], v[136:137] op_sel_hi:[1,0]
	ds_read_b128 v[196:199], v2 offset:5104
	s_waitcnt lgkmcnt(10)
	v_pk_fma_f32 v[142:143], v[150:151], v[210:211], v[142:143] op_sel_hi:[1,0,1]
	v_pk_fma_f32 v[144:145], v[152:153], v[210:211], v[144:145] op_sel_hi:[1,0,1]
	v_pk_fma_f32 v[146:147], v[154:155], v[210:211], v[146:147] op_sel_hi:[1,0,1]
	v_pk_fma_f32 v[148:149], v[156:157], v[210:211], v[148:149] op_sel_hi:[1,0,1]
	ds_read_b32 v212, v104 offset:5600
	ds_read_b128 v[166:169], v2 offset:4320
	s_waitcnt lgkmcnt(10)
	v_pk_fma_f32 v[96:97], v[96:97], v[126:127], v[142:143]
	v_pk_fma_f32 v[98:99], v[98:99], v[128:129], v[144:145]
	v_pk_fma_f32 v[100:101], v[100:101], v[130:131], v[146:147]
	v_pk_fma_f32 v[102:103], v[102:103], v[132:133], v[148:149]
	ds_read_b128 v[170:173], v2 offset:4336
	ds_read_b128 v[200:203], v2 offset:5344
	ds_read_b128 v[204:207], v2 offset:5360
	s_waitcnt lgkmcnt(9)
	v_pk_mul_f32 v[174:175], v[96:97], v[174:175]
	v_pk_mul_f32 v[158:159], v[96:97], v[158:159]
	v_pk_fma_f32 v[174:175], v[98:99], v[176:177], v[174:175]
	v_pk_fma_f32 v[158:159], v[98:99], v[160:161], v[158:159]
	v_pk_fma_f32 v[174:175], v[100:101], v[178:179], v[174:175]
	v_pk_fma_f32 v[158:159], v[100:101], v[162:163], v[158:159]
	v_pk_fma_f32 v[174:175], v[102:103], v[180:181], v[174:175]
	v_pk_fma_f32 v[158:159], v[102:103], v[164:165], v[158:159]
	v_add_f32_e32 v176, v174, v175
	v_add_f32_e32 v214, v158, v159
	ds_read_b128 v[134:137], v2 offset:6016
	v_add_f32_dpp v176, v176, v176 quad_perm:[1,0,3,2] row_mask:0xf bank_mask:0xf bound_ctrl:1
	ds_read_b128 v[138:141], v2 offset:6032
	ds_read_b128 v[142:145], v2 offset:6272
	v_add_f32_dpp v176, v176, v176 quad_perm:[2,3,0,1] row_mask:0xf bank_mask:0xf bound_ctrl:1
	ds_read_b128 v[146:149], v2 offset:6288
	ds_read_b128 v[150:153], v2 offset:6528
	v_add_f32_dpp v176, v176, v176 row_half_mirror row_mask:0xf bank_mask:0xf bound_ctrl:1
	s_waitcnt lgkmcnt(12)
	v_pk_mul_f32 v[182:183], v[182:183], v[176:177] op_sel_hi:[1,0]
	v_pk_mul_f32 v[184:185], v[184:185], v[176:177] op_sel_hi:[1,0]
	v_pk_mul_f32 v[186:187], v[186:187], v[176:177] op_sel_hi:[1,0]
	v_pk_mul_f32 v[188:189], v[188:189], v[176:177] op_sel_hi:[1,0]
	ds_read_b128 v[154:157], v2 offset:6544
	s_waitcnt lgkmcnt(10)
	v_pk_fma_f32 v[182:183], v[192:193], v[212:213], v[182:183] op_sel_hi:[1,0,1]
	v_pk_fma_f32 v[184:185], v[194:195], v[212:213], v[184:185] op_sel_hi:[1,0,1]
	v_pk_fma_f32 v[186:187], v[196:197], v[212:213], v[186:187] op_sel_hi:[1,0,1]
	v_pk_fma_f32 v[188:189], v[198:199], v[212:213], v[188:189] op_sel_hi:[1,0,1]
	ds_read_b32 v210, v104 offset:7040
	ds_read_b128 v[126:129], v2 offset:5760
	s_waitcnt lgkmcnt(10)
	v_pk_fma_f32 v[96:97], v[96:97], v[166:167], v[182:183]
	v_pk_fma_f32 v[98:99], v[98:99], v[168:169], v[184:185]
	v_pk_fma_f32 v[100:101], v[100:101], v[170:171], v[186:187]
	v_pk_fma_f32 v[102:103], v[102:103], v[172:173], v[188:189]
	ds_read_b128 v[130:133], v2 offset:5776
	ds_read_b128 v[158:161], v2 offset:6784
	ds_read_b128 v[162:165], v2 offset:6800
	s_waitcnt lgkmcnt(9)
	v_pk_mul_f32 v[134:135], v[96:97], v[134:135]
	v_pk_mul_f32 v[200:201], v[96:97], v[200:201]
	v_pk_fma_f32 v[134:135], v[98:99], v[136:137], v[134:135]
	v_pk_fma_f32 v[200:201], v[98:99], v[202:203], v[200:201]
	v_pk_fma_f32 v[134:135], v[100:101], v[138:139], v[134:135]
	v_pk_fma_f32 v[200:201], v[100:101], v[204:205], v[200:201]
	v_pk_fma_f32 v[134:135], v[102:103], v[140:141], v[134:135]
	v_pk_fma_f32 v[200:201], v[102:103], v[206:207], v[200:201]
	v_add_f32_e32 v136, v134, v135
	v_add_f32_e32 v215, v200, v201
	ds_read_b128 v[174:177], v2 offset:7456
	v_add_f32_dpp v136, v136, v136 quad_perm:[1,0,3,2] row_mask:0xf bank_mask:0xf bound_ctrl:1
	ds_read_b128 v[178:181], v2 offset:7472
	ds_read_b128 v[182:185], v2 offset:7712
	v_add_f32_dpp v136, v136, v136 quad_perm:[2,3,0,1] row_mask:0xf bank_mask:0xf bound_ctrl:1
	ds_read_b128 v[186:189], v2 offset:7728
	ds_read_b128 v[192:195], v2 offset:7968
	v_add_f32_dpp v136, v136, v136 row_half_mirror row_mask:0xf bank_mask:0xf bound_ctrl:1
	s_waitcnt lgkmcnt(12)
	v_pk_mul_f32 v[142:143], v[142:143], v[136:137] op_sel_hi:[1,0]
	v_pk_mul_f32 v[144:145], v[144:145], v[136:137] op_sel_hi:[1,0]
	v_pk_mul_f32 v[146:147], v[146:147], v[136:137] op_sel_hi:[1,0]
	v_pk_mul_f32 v[148:149], v[148:149], v[136:137] op_sel_hi:[1,0]
	ds_read_b128 v[196:199], v2 offset:7984
	s_waitcnt lgkmcnt(10)
	v_pk_fma_f32 v[142:143], v[150:151], v[210:211], v[142:143] op_sel_hi:[1,0,1]
	v_pk_fma_f32 v[144:145], v[152:153], v[210:211], v[144:145] op_sel_hi:[1,0,1]
	v_pk_fma_f32 v[146:147], v[154:155], v[210:211], v[146:147] op_sel_hi:[1,0,1]
	v_pk_fma_f32 v[148:149], v[156:157], v[210:211], v[148:149] op_sel_hi:[1,0,1]
	ds_read_b32 v212, v104 offset:8480
	ds_read_b128 v[166:169], v2 offset:7200
	s_waitcnt lgkmcnt(10)
	v_pk_fma_f32 v[96:97], v[96:97], v[126:127], v[142:143]
	v_pk_fma_f32 v[98:99], v[98:99], v[128:129], v[144:145]
	v_pk_fma_f32 v[100:101], v[100:101], v[130:131], v[146:147]
	v_pk_fma_f32 v[102:103], v[102:103], v[132:133], v[148:149]
	ds_read_b128 v[170:173], v2 offset:7216
	ds_read_b128 v[200:203], v2 offset:8224
	ds_read_b128 v[204:207], v2 offset:8240
	s_waitcnt lgkmcnt(9)
	v_pk_mul_f32 v[174:175], v[96:97], v[174:175]
	v_pk_mul_f32 v[158:159], v[96:97], v[158:159]
	v_pk_fma_f32 v[174:175], v[98:99], v[176:177], v[174:175]
	v_pk_fma_f32 v[158:159], v[98:99], v[160:161], v[158:159]
	v_pk_fma_f32 v[174:175], v[100:101], v[178:179], v[174:175]
	v_pk_fma_f32 v[158:159], v[100:101], v[162:163], v[158:159]
	v_pk_fma_f32 v[174:175], v[102:103], v[180:181], v[174:175]
	v_pk_fma_f32 v[158:159], v[102:103], v[164:165], v[158:159]
	v_add_f32_e32 v176, v174, v175
	v_add_f32_e32 v216, v158, v159
	ds_read_b128 v[134:137], v2 offset:8896
	v_add_f32_dpp v176, v176, v176 quad_perm:[1,0,3,2] row_mask:0xf bank_mask:0xf bound_ctrl:1
	ds_read_b128 v[138:141], v2 offset:8912
	ds_read_b128 v[142:145], v2 offset:9152
	v_add_f32_dpp v176, v176, v176 quad_perm:[2,3,0,1] row_mask:0xf bank_mask:0xf bound_ctrl:1
	ds_read_b128 v[146:149], v2 offset:9168
	ds_read_b128 v[150:153], v2 offset:9408
	v_add_f32_dpp v176, v176, v176 row_half_mirror row_mask:0xf bank_mask:0xf bound_ctrl:1
	s_waitcnt lgkmcnt(12)
	v_pk_mul_f32 v[182:183], v[182:183], v[176:177] op_sel_hi:[1,0]
	v_pk_mul_f32 v[184:185], v[184:185], v[176:177] op_sel_hi:[1,0]
	v_pk_mul_f32 v[186:187], v[186:187], v[176:177] op_sel_hi:[1,0]
	v_pk_mul_f32 v[188:189], v[188:189], v[176:177] op_sel_hi:[1,0]
	ds_read_b128 v[154:157], v2 offset:9424
	s_waitcnt lgkmcnt(10)
	v_pk_fma_f32 v[182:183], v[192:193], v[212:213], v[182:183] op_sel_hi:[1,0,1]
	v_pk_fma_f32 v[184:185], v[194:195], v[212:213], v[184:185] op_sel_hi:[1,0,1]
	v_pk_fma_f32 v[186:187], v[196:197], v[212:213], v[186:187] op_sel_hi:[1,0,1]
	v_pk_fma_f32 v[188:189], v[198:199], v[212:213], v[188:189] op_sel_hi:[1,0,1]
	ds_read_b32 v210, v104 offset:9920
	ds_read_b128 v[126:129], v2 offset:8640
	s_waitcnt lgkmcnt(10)
	v_pk_fma_f32 v[96:97], v[96:97], v[166:167], v[182:183]
	v_pk_fma_f32 v[98:99], v[98:99], v[168:169], v[184:185]
	v_pk_fma_f32 v[100:101], v[100:101], v[170:171], v[186:187]
	v_pk_fma_f32 v[102:103], v[102:103], v[172:173], v[188:189]
	ds_read_b128 v[130:133], v2 offset:8656
	ds_read_b128 v[158:161], v2 offset:9664
	ds_read_b128 v[162:165], v2 offset:9680
	s_waitcnt lgkmcnt(9)
	v_pk_mul_f32 v[134:135], v[96:97], v[134:135]
	v_pk_mul_f32 v[200:201], v[96:97], v[200:201]
	v_pk_fma_f32 v[134:135], v[98:99], v[136:137], v[134:135]
	v_pk_fma_f32 v[200:201], v[98:99], v[202:203], v[200:201]
	v_pk_fma_f32 v[134:135], v[100:101], v[138:139], v[134:135]
	v_pk_fma_f32 v[200:201], v[100:101], v[204:205], v[200:201]
	v_pk_fma_f32 v[134:135], v[102:103], v[140:141], v[134:135]
	v_pk_fma_f32 v[200:201], v[102:103], v[206:207], v[200:201]
	v_add_f32_e32 v136, v134, v135
	v_add_f32_e32 v208, v200, v201
	ds_read_b128 v[174:177], v2 offset:10336
	v_add_f32_dpp v136, v136, v136 quad_perm:[1,0,3,2] row_mask:0xf bank_mask:0xf bound_ctrl:1
	ds_read_b128 v[178:181], v2 offset:10352
	ds_read_b128 v[182:185], v2 offset:10592
	v_add_f32_dpp v136, v136, v136 quad_perm:[2,3,0,1] row_mask:0xf bank_mask:0xf bound_ctrl:1
	ds_read_b128 v[186:189], v2 offset:10608
	ds_read_b128 v[192:195], v2 offset:10848
	v_add_f32_dpp v136, v136, v136 row_half_mirror row_mask:0xf bank_mask:0xf bound_ctrl:1
	s_waitcnt lgkmcnt(12)
	v_pk_mul_f32 v[142:143], v[142:143], v[136:137] op_sel_hi:[1,0]
	v_pk_mul_f32 v[144:145], v[144:145], v[136:137] op_sel_hi:[1,0]
	v_pk_mul_f32 v[146:147], v[146:147], v[136:137] op_sel_hi:[1,0]
	v_pk_mul_f32 v[148:149], v[148:149], v[136:137] op_sel_hi:[1,0]
	ds_read_b128 v[196:199], v2 offset:10864
	s_waitcnt lgkmcnt(10)
	v_pk_fma_f32 v[142:143], v[150:151], v[210:211], v[142:143] op_sel_hi:[1,0,1]
	v_pk_fma_f32 v[144:145], v[152:153], v[210:211], v[144:145] op_sel_hi:[1,0,1]
	v_pk_fma_f32 v[146:147], v[154:155], v[210:211], v[146:147] op_sel_hi:[1,0,1]
	v_pk_fma_f32 v[148:149], v[156:157], v[210:211], v[148:149] op_sel_hi:[1,0,1]
	ds_read_b32 v212, v104 offset:11360
	ds_read_b128 v[166:169], v2 offset:10080
	s_waitcnt lgkmcnt(10)
	v_pk_fma_f32 v[96:97], v[96:97], v[126:127], v[142:143]
	v_pk_fma_f32 v[98:99], v[98:99], v[128:129], v[144:145]
	v_pk_fma_f32 v[100:101], v[100:101], v[130:131], v[146:147]
	v_pk_fma_f32 v[102:103], v[102:103], v[132:133], v[148:149]
	ds_read_b128 v[170:173], v2 offset:10096
	ds_read_b128 v[200:203], v2 offset:11104
	ds_read_b128 v[204:207], v2 offset:11120
	s_waitcnt lgkmcnt(9)
	v_pk_mul_f32 v[174:175], v[96:97], v[174:175]
	v_pk_mul_f32 v[158:159], v[96:97], v[158:159]
	v_pk_fma_f32 v[174:175], v[98:99], v[176:177], v[174:175]
	v_pk_fma_f32 v[158:159], v[98:99], v[160:161], v[158:159]
	v_pk_fma_f32 v[174:175], v[100:101], v[178:179], v[174:175]
	v_pk_fma_f32 v[158:159], v[100:101], v[162:163], v[158:159]
	v_pk_fma_f32 v[174:175], v[102:103], v[180:181], v[174:175]
	v_pk_fma_f32 v[158:159], v[102:103], v[164:165], v[158:159]
	v_add_f32_e32 v176, v174, v175
	v_add_f32_e32 v191, v158, v159
	ds_read_b128 v[134:137], v2 offset:11776
	v_add_f32_dpp v176, v176, v176 quad_perm:[1,0,3,2] row_mask:0xf bank_mask:0xf bound_ctrl:1
	ds_read_b128 v[138:141], v2 offset:11792
	ds_read_b128 v[142:145], v2 offset:12032
	v_add_f32_dpp v176, v176, v176 quad_perm:[2,3,0,1] row_mask:0xf bank_mask:0xf bound_ctrl:1
	ds_read_b128 v[146:149], v2 offset:12048
	ds_read_b128 v[150:153], v2 offset:12288
	v_add_f32_dpp v176, v176, v176 row_half_mirror row_mask:0xf bank_mask:0xf bound_ctrl:1
	s_waitcnt lgkmcnt(12)
	v_pk_mul_f32 v[182:183], v[182:183], v[176:177] op_sel_hi:[1,0]
	v_pk_mul_f32 v[184:185], v[184:185], v[176:177] op_sel_hi:[1,0]
	v_pk_mul_f32 v[186:187], v[186:187], v[176:177] op_sel_hi:[1,0]
	v_pk_mul_f32 v[188:189], v[188:189], v[176:177] op_sel_hi:[1,0]
	ds_read_b128 v[154:157], v2 offset:12304
	s_waitcnt lgkmcnt(10)
	v_pk_fma_f32 v[182:183], v[192:193], v[212:213], v[182:183] op_sel_hi:[1,0,1]
	v_pk_fma_f32 v[184:185], v[194:195], v[212:213], v[184:185] op_sel_hi:[1,0,1]
	v_pk_fma_f32 v[186:187], v[196:197], v[212:213], v[186:187] op_sel_hi:[1,0,1]
	v_pk_fma_f32 v[188:189], v[198:199], v[212:213], v[188:189] op_sel_hi:[1,0,1]
	ds_read_b32 v210, v104 offset:12800
	ds_read_b128 v[126:129], v2 offset:11520
	s_waitcnt lgkmcnt(10)
	v_pk_fma_f32 v[96:97], v[96:97], v[166:167], v[182:183]
	v_pk_fma_f32 v[98:99], v[98:99], v[168:169], v[184:185]
	v_pk_fma_f32 v[100:101], v[100:101], v[170:171], v[186:187]
	v_pk_fma_f32 v[102:103], v[102:103], v[172:173], v[188:189]
	ds_read_b128 v[130:133], v2 offset:11536
	ds_read_b128 v[158:161], v2 offset:12544
	ds_read_b128 v[162:165], v2 offset:12560
	s_waitcnt lgkmcnt(9)
	v_pk_mul_f32 v[134:135], v[96:97], v[134:135]
	v_pk_mul_f32 v[200:201], v[96:97], v[200:201]
	v_pk_fma_f32 v[134:135], v[98:99], v[136:137], v[134:135]
	v_pk_fma_f32 v[200:201], v[98:99], v[202:203], v[200:201]
	v_pk_fma_f32 v[134:135], v[100:101], v[138:139], v[134:135]
	v_pk_fma_f32 v[200:201], v[100:101], v[204:205], v[200:201]
	v_pk_fma_f32 v[134:135], v[102:103], v[140:141], v[134:135]
	v_pk_fma_f32 v[200:201], v[102:103], v[206:207], v[200:201]
	v_add_f32_e32 v136, v134, v135
	v_add_f32_e32 v59, v200, v201
	ds_read_b128 v[174:177], v2 offset:13216
	v_add_f32_dpp v136, v136, v136 quad_perm:[1,0,3,2] row_mask:0xf bank_mask:0xf bound_ctrl:1
	ds_read_b128 v[178:181], v2 offset:13232
	ds_read_b128 v[182:185], v2 offset:13472
	v_add_f32_dpp v136, v136, v136 quad_perm:[2,3,0,1] row_mask:0xf bank_mask:0xf bound_ctrl:1
	ds_read_b128 v[186:189], v2 offset:13488
	ds_read_b128 v[192:195], v2 offset:13728
	v_add_f32_dpp v136, v136, v136 row_half_mirror row_mask:0xf bank_mask:0xf bound_ctrl:1
	v_cndmask_b32_e64 v200, v213, v211, s[10:11]
	v_cndmask_b32_e64 v204, v211, v213, s[10:11]
	v_cndmask_b32_e64 v201, v215, v214, s[10:11]
	v_cndmask_b32_e64 v205, v214, v215, s[10:11]
	v_cndmask_b32_e64 v202, v208, v216, s[10:11]
	v_cndmask_b32_e64 v206, v216, v208, s[10:11]
	v_cndmask_b32_e64 v203, v59, v191, s[10:11]
	v_cndmask_b32_e64 v207, v191, v59, s[10:11]
	v_add_f32_dpp v200, v204, v200 quad_perm:[1,0,3,2] row_mask:0xf bank_mask:0xf bound_ctrl:1
	v_add_f32_dpp v201, v205, v201 quad_perm:[1,0,3,2] row_mask:0xf bank_mask:0xf bound_ctrl:1
	v_add_f32_dpp v202, v206, v202 quad_perm:[1,0,3,2] row_mask:0xf bank_mask:0xf bound_ctrl:1
	v_add_f32_dpp v203, v207, v203 quad_perm:[1,0,3,2] row_mask:0xf bank_mask:0xf bound_ctrl:1
	v_cndmask_b32_e64 v204, v201, v200, s[12:13]
	v_cndmask_b32_e64 v206, v200, v201, s[12:13]
	v_cndmask_b32_e64 v205, v203, v202, s[12:13]
	v_cndmask_b32_e64 v207, v202, v203, s[12:13]
	v_add_f32_dpp v204, v206, v204 quad_perm:[2,3,0,1] row_mask:0xf bank_mask:0xf bound_ctrl:1
	s_nop 0
	v_add_f32_dpp v205, v207, v205 quad_perm:[2,3,0,1] row_mask:0xf bank_mask:0xf bound_ctrl:1
	v_xor_b32_e32 v202, 4, v121
	v_cndmask_b32_e64 v200, v205, v204, s[14:15]
	v_cndmask_b32_e64 v201, v204, v205, s[14:15]
	v_lshlrev_b32_e32 v202, 2, v202
	ds_bpermute_b32 v201, v202, v201
	s_waitcnt lgkmcnt(0)
	v_add_f32_e32 v200, v200, v201
	ds_write_b32 v105, v200
	v_pk_mul_f32 v[142:143], v[142:143], v[136:137] op_sel_hi:[1,0]
	v_pk_mul_f32 v[144:145], v[144:145], v[136:137] op_sel_hi:[1,0]
	v_pk_mul_f32 v[146:147], v[146:147], v[136:137] op_sel_hi:[1,0]
	v_pk_mul_f32 v[148:149], v[148:149], v[136:137] op_sel_hi:[1,0]
	ds_read_b128 v[196:199], v2 offset:13744
	v_pk_fma_f32 v[142:143], v[150:151], v[210:211], v[142:143] op_sel_hi:[1,0,1]
	v_pk_fma_f32 v[144:145], v[152:153], v[210:211], v[144:145] op_sel_hi:[1,0,1]
	v_pk_fma_f32 v[146:147], v[154:155], v[210:211], v[146:147] op_sel_hi:[1,0,1]
	v_pk_fma_f32 v[148:149], v[156:157], v[210:211], v[148:149] op_sel_hi:[1,0,1]
	ds_read_b32 v212, v104 offset:14240
	ds_read_b128 v[166:169], v2 offset:12960
	v_pk_fma_f32 v[96:97], v[96:97], v[126:127], v[142:143]
	v_pk_fma_f32 v[98:99], v[98:99], v[128:129], v[144:145]
	v_pk_fma_f32 v[100:101], v[100:101], v[130:131], v[146:147]
	v_pk_fma_f32 v[102:103], v[102:103], v[132:133], v[148:149]
	ds_read_b128 v[170:173], v2 offset:12976
	ds_read_b128 v[200:203], v2 offset:13984
	ds_read_b128 v[204:207], v2 offset:14000
	v_pk_mul_f32 v[174:175], v[96:97], v[174:175]
	v_pk_mul_f32 v[158:159], v[96:97], v[158:159]
	v_pk_fma_f32 v[174:175], v[98:99], v[176:177], v[174:175]
	v_pk_fma_f32 v[158:159], v[98:99], v[160:161], v[158:159]
	v_pk_fma_f32 v[174:175], v[100:101], v[178:179], v[174:175]
	v_pk_fma_f32 v[158:159], v[100:101], v[162:163], v[158:159]
	v_pk_fma_f32 v[174:175], v[102:103], v[180:181], v[174:175]
	v_pk_fma_f32 v[158:159], v[102:103], v[164:165], v[158:159]
	v_add_f32_e32 v176, v174, v175
	v_add_f32_e32 v211, v158, v159
	ds_read_b128 v[134:137], v2 offset:14656
	v_add_f32_dpp v176, v176, v176 quad_perm:[1,0,3,2] row_mask:0xf bank_mask:0xf bound_ctrl:1
	ds_read_b128 v[138:141], v2 offset:14672
	ds_read_b128 v[142:145], v2 offset:14912
	v_add_f32_dpp v176, v176, v176 quad_perm:[2,3,0,1] row_mask:0xf bank_mask:0xf bound_ctrl:1
	ds_read_b128 v[146:149], v2 offset:14928
	ds_read_b128 v[150:153], v2 offset:15168
	v_add_f32_dpp v176, v176, v176 row_half_mirror row_mask:0xf bank_mask:0xf bound_ctrl:1
	v_pk_mul_f32 v[182:183], v[182:183], v[176:177] op_sel_hi:[1,0]
	v_pk_mul_f32 v[184:185], v[184:185], v[176:177] op_sel_hi:[1,0]
	v_pk_mul_f32 v[186:187], v[186:187], v[176:177] op_sel_hi:[1,0]
	v_pk_mul_f32 v[188:189], v[188:189], v[176:177] op_sel_hi:[1,0]
	ds_read_b128 v[154:157], v2 offset:15184
	s_waitcnt lgkmcnt(10)
	v_pk_fma_f32 v[182:183], v[192:193], v[212:213], v[182:183] op_sel_hi:[1,0,1]
	v_pk_fma_f32 v[184:185], v[194:195], v[212:213], v[184:185] op_sel_hi:[1,0,1]
	v_pk_fma_f32 v[186:187], v[196:197], v[212:213], v[186:187] op_sel_hi:[1,0,1]
	v_pk_fma_f32 v[188:189], v[198:199], v[212:213], v[188:189] op_sel_hi:[1,0,1]
	ds_read_b32 v210, v104 offset:15680
	ds_read_b128 v[126:129], v2 offset:14400
	s_waitcnt lgkmcnt(10)
	v_pk_fma_f32 v[96:97], v[96:97], v[166:167], v[182:183]
	v_pk_fma_f32 v[98:99], v[98:99], v[168:169], v[184:185]
	v_pk_fma_f32 v[100:101], v[100:101], v[170:171], v[186:187]
	v_pk_fma_f32 v[102:103], v[102:103], v[172:173], v[188:189]
	ds_read_b128 v[130:133], v2 offset:14416
	ds_read_b128 v[158:161], v2 offset:15424
	ds_read_b128 v[162:165], v2 offset:15440
	s_waitcnt lgkmcnt(9)
	v_pk_mul_f32 v[134:135], v[96:97], v[134:135]
	v_pk_mul_f32 v[200:201], v[96:97], v[200:201]
	v_pk_fma_f32 v[134:135], v[98:99], v[136:137], v[134:135]
	v_pk_fma_f32 v[200:201], v[98:99], v[202:203], v[200:201]
	v_pk_fma_f32 v[134:135], v[100:101], v[138:139], v[134:135]
	v_pk_fma_f32 v[200:201], v[100:101], v[204:205], v[200:201]
	v_pk_fma_f32 v[134:135], v[102:103], v[140:141], v[134:135]
	v_pk_fma_f32 v[200:201], v[102:103], v[206:207], v[200:201]
	v_add_f32_e32 v136, v134, v135
	v_add_f32_e32 v213, v200, v201
	ds_read_b128 v[174:177], v2 offset:16096
	v_add_f32_dpp v136, v136, v136 quad_perm:[1,0,3,2] row_mask:0xf bank_mask:0xf bound_ctrl:1
	ds_read_b128 v[178:181], v2 offset:16112
	ds_read_b128 v[182:185], v2 offset:16352
	v_add_f32_dpp v136, v136, v136 quad_perm:[2,3,0,1] row_mask:0xf bank_mask:0xf bound_ctrl:1
	ds_read_b128 v[186:189], v2 offset:16368
	ds_read_b128 v[192:195], v2 offset:16608
	v_add_f32_dpp v136, v136, v136 row_half_mirror row_mask:0xf bank_mask:0xf bound_ctrl:1
	s_waitcnt lgkmcnt(12)
	v_pk_mul_f32 v[142:143], v[142:143], v[136:137] op_sel_hi:[1,0]
	v_pk_mul_f32 v[144:145], v[144:145], v[136:137] op_sel_hi:[1,0]
	v_pk_mul_f32 v[146:147], v[146:147], v[136:137] op_sel_hi:[1,0]
	v_pk_mul_f32 v[148:149], v[148:149], v[136:137] op_sel_hi:[1,0]
	ds_read_b128 v[196:199], v2 offset:16624
	s_waitcnt lgkmcnt(10)
	v_pk_fma_f32 v[142:143], v[150:151], v[210:211], v[142:143] op_sel_hi:[1,0,1]
	v_pk_fma_f32 v[144:145], v[152:153], v[210:211], v[144:145] op_sel_hi:[1,0,1]
	v_pk_fma_f32 v[146:147], v[154:155], v[210:211], v[146:147] op_sel_hi:[1,0,1]
	v_pk_fma_f32 v[148:149], v[156:157], v[210:211], v[148:149] op_sel_hi:[1,0,1]
	ds_read_b32 v212, v104 offset:17120
	ds_read_b128 v[166:169], v2 offset:15840
	s_waitcnt lgkmcnt(10)
	v_pk_fma_f32 v[96:97], v[96:97], v[126:127], v[142:143]
	v_pk_fma_f32 v[98:99], v[98:99], v[128:129], v[144:145]
	v_pk_fma_f32 v[100:101], v[100:101], v[130:131], v[146:147]
	v_pk_fma_f32 v[102:103], v[102:103], v[132:133], v[148:149]
	ds_read_b128 v[170:173], v2 offset:15856
	ds_read_b128 v[200:203], v2 offset:16864
	ds_read_b128 v[204:207], v2 offset:16880
	s_waitcnt lgkmcnt(9)
	v_pk_mul_f32 v[174:175], v[96:97], v[174:175]
	v_pk_mul_f32 v[158:159], v[96:97], v[158:159]
	v_pk_fma_f32 v[174:175], v[98:99], v[176:177], v[174:175]
	v_pk_fma_f32 v[158:159], v[98:99], v[160:161], v[158:159]
	v_pk_fma_f32 v[174:175], v[100:101], v[178:179], v[174:175]
	v_pk_fma_f32 v[158:159], v[100:101], v[162:163], v[158:159]
	v_pk_fma_f32 v[174:175], v[102:103], v[180:181], v[174:175]
	v_pk_fma_f32 v[158:159], v[102:103], v[164:165], v[158:159]
	v_add_f32_e32 v176, v174, v175
	v_add_f32_e32 v214, v158, v159
	ds_read_b128 v[134:137], v2 offset:17536
	v_add_f32_dpp v176, v176, v176 quad_perm:[1,0,3,2] row_mask:0xf bank_mask:0xf bound_ctrl:1
	ds_read_b128 v[138:141], v2 offset:17552
	ds_read_b128 v[142:145], v2 offset:17792
	v_add_f32_dpp v176, v176, v176 quad_perm:[2,3,0,1] row_mask:0xf bank_mask:0xf bound_ctrl:1
	ds_read_b128 v[146:149], v2 offset:17808
	ds_read_b128 v[150:153], v2 offset:18048
	v_add_f32_dpp v176, v176, v176 row_half_mirror row_mask:0xf bank_mask:0xf bound_ctrl:1
	s_waitcnt lgkmcnt(12)
	v_pk_mul_f32 v[182:183], v[182:183], v[176:177] op_sel_hi:[1,0]
	v_pk_mul_f32 v[184:185], v[184:185], v[176:177] op_sel_hi:[1,0]
	v_pk_mul_f32 v[186:187], v[186:187], v[176:177] op_sel_hi:[1,0]
	v_pk_mul_f32 v[188:189], v[188:189], v[176:177] op_sel_hi:[1,0]
	ds_read_b128 v[154:157], v2 offset:18064
	s_waitcnt lgkmcnt(10)
	v_pk_fma_f32 v[182:183], v[192:193], v[212:213], v[182:183] op_sel_hi:[1,0,1]
	v_pk_fma_f32 v[184:185], v[194:195], v[212:213], v[184:185] op_sel_hi:[1,0,1]
	v_pk_fma_f32 v[186:187], v[196:197], v[212:213], v[186:187] op_sel_hi:[1,0,1]
	v_pk_fma_f32 v[188:189], v[198:199], v[212:213], v[188:189] op_sel_hi:[1,0,1]
	ds_read_b32 v210, v104 offset:18560
	ds_read_b128 v[126:129], v2 offset:17280
	s_waitcnt lgkmcnt(10)
	v_pk_fma_f32 v[96:97], v[96:97], v[166:167], v[182:183]
	v_pk_fma_f32 v[98:99], v[98:99], v[168:169], v[184:185]
	v_pk_fma_f32 v[100:101], v[100:101], v[170:171], v[186:187]
	v_pk_fma_f32 v[102:103], v[102:103], v[172:173], v[188:189]
	ds_read_b128 v[130:133], v2 offset:17296
	ds_read_b128 v[158:161], v2 offset:18304
	ds_read_b128 v[162:165], v2 offset:18320
	s_waitcnt lgkmcnt(9)
	v_pk_mul_f32 v[134:135], v[96:97], v[134:135]
	v_pk_mul_f32 v[200:201], v[96:97], v[200:201]
	v_pk_fma_f32 v[134:135], v[98:99], v[136:137], v[134:135]
	v_pk_fma_f32 v[200:201], v[98:99], v[202:203], v[200:201]
	v_pk_fma_f32 v[134:135], v[100:101], v[138:139], v[134:135]
	v_pk_fma_f32 v[200:201], v[100:101], v[204:205], v[200:201]
	v_pk_fma_f32 v[134:135], v[102:103], v[140:141], v[134:135]
	v_pk_fma_f32 v[200:201], v[102:103], v[206:207], v[200:201]
	v_add_f32_e32 v136, v134, v135
	v_add_f32_e32 v215, v200, v201
	ds_read_b128 v[174:177], v2 offset:18976
	v_add_f32_dpp v136, v136, v136 quad_perm:[1,0,3,2] row_mask:0xf bank_mask:0xf bound_ctrl:1
	ds_read_b128 v[178:181], v2 offset:18992
	ds_read_b128 v[182:185], v2 offset:19232
	v_add_f32_dpp v136, v136, v136 quad_perm:[2,3,0,1] row_mask:0xf bank_mask:0xf bound_ctrl:1
	ds_read_b128 v[186:189], v2 offset:19248
	ds_read_b128 v[192:195], v2 offset:19488
	v_add_f32_dpp v136, v136, v136 row_half_mirror row_mask:0xf bank_mask:0xf bound_ctrl:1
	s_waitcnt lgkmcnt(12)
	v_pk_mul_f32 v[142:143], v[142:143], v[136:137] op_sel_hi:[1,0]
	v_pk_mul_f32 v[144:145], v[144:145], v[136:137] op_sel_hi:[1,0]
	v_pk_mul_f32 v[146:147], v[146:147], v[136:137] op_sel_hi:[1,0]
	v_pk_mul_f32 v[148:149], v[148:149], v[136:137] op_sel_hi:[1,0]
	ds_read_b128 v[196:199], v2 offset:19504
	s_waitcnt lgkmcnt(10)
	v_pk_fma_f32 v[142:143], v[150:151], v[210:211], v[142:143] op_sel_hi:[1,0,1]
	v_pk_fma_f32 v[144:145], v[152:153], v[210:211], v[144:145] op_sel_hi:[1,0,1]
	v_pk_fma_f32 v[146:147], v[154:155], v[210:211], v[146:147] op_sel_hi:[1,0,1]
	v_pk_fma_f32 v[148:149], v[156:157], v[210:211], v[148:149] op_sel_hi:[1,0,1]
	ds_read_b32 v212, v104 offset:20000
	ds_read_b128 v[166:169], v2 offset:18720
	s_waitcnt lgkmcnt(10)
	v_pk_fma_f32 v[96:97], v[96:97], v[126:127], v[142:143]
	v_pk_fma_f32 v[98:99], v[98:99], v[128:129], v[144:145]
	v_pk_fma_f32 v[100:101], v[100:101], v[130:131], v[146:147]
	v_pk_fma_f32 v[102:103], v[102:103], v[132:133], v[148:149]
	ds_read_b128 v[170:173], v2 offset:18736
	ds_read_b128 v[200:203], v2 offset:19744
	ds_read_b128 v[204:207], v2 offset:19760
	s_waitcnt lgkmcnt(9)
	v_pk_mul_f32 v[174:175], v[96:97], v[174:175]
	v_pk_mul_f32 v[158:159], v[96:97], v[158:159]
	v_pk_fma_f32 v[174:175], v[98:99], v[176:177], v[174:175]
	v_pk_fma_f32 v[158:159], v[98:99], v[160:161], v[158:159]
	v_pk_fma_f32 v[174:175], v[100:101], v[178:179], v[174:175]
	v_pk_fma_f32 v[158:159], v[100:101], v[162:163], v[158:159]
	v_pk_fma_f32 v[174:175], v[102:103], v[180:181], v[174:175]
	v_pk_fma_f32 v[158:159], v[102:103], v[164:165], v[158:159]
	v_add_f32_e32 v176, v174, v175
	v_add_f32_e32 v216, v158, v159
	ds_read_b128 v[134:137], v2 offset:20416
	v_add_f32_dpp v176, v176, v176 quad_perm:[1,0,3,2] row_mask:0xf bank_mask:0xf bound_ctrl:1
	ds_read_b128 v[138:141], v2 offset:20432
	ds_read_b128 v[142:145], v2 offset:20672
	v_add_f32_dpp v176, v176, v176 quad_perm:[2,3,0,1] row_mask:0xf bank_mask:0xf bound_ctrl:1
	ds_read_b128 v[146:149], v2 offset:20688
	ds_read_b128 v[150:153], v2 offset:20928
	v_add_f32_dpp v176, v176, v176 row_half_mirror row_mask:0xf bank_mask:0xf bound_ctrl:1
	s_waitcnt lgkmcnt(12)
	v_pk_mul_f32 v[182:183], v[182:183], v[176:177] op_sel_hi:[1,0]
	v_pk_mul_f32 v[184:185], v[184:185], v[176:177] op_sel_hi:[1,0]
	v_pk_mul_f32 v[186:187], v[186:187], v[176:177] op_sel_hi:[1,0]
	v_pk_mul_f32 v[188:189], v[188:189], v[176:177] op_sel_hi:[1,0]
	ds_read_b128 v[154:157], v2 offset:20944
	s_waitcnt lgkmcnt(10)
	v_pk_fma_f32 v[182:183], v[192:193], v[212:213], v[182:183] op_sel_hi:[1,0,1]
	v_pk_fma_f32 v[184:185], v[194:195], v[212:213], v[184:185] op_sel_hi:[1,0,1]
	v_pk_fma_f32 v[186:187], v[196:197], v[212:213], v[186:187] op_sel_hi:[1,0,1]
	v_pk_fma_f32 v[188:189], v[198:199], v[212:213], v[188:189] op_sel_hi:[1,0,1]
	ds_read_b32 v210, v104 offset:21440
	ds_read_b128 v[126:129], v2 offset:20160
	s_waitcnt lgkmcnt(10)
	v_pk_fma_f32 v[96:97], v[96:97], v[166:167], v[182:183]
	v_pk_fma_f32 v[98:99], v[98:99], v[168:169], v[184:185]
	v_pk_fma_f32 v[100:101], v[100:101], v[170:171], v[186:187]
	v_pk_fma_f32 v[102:103], v[102:103], v[172:173], v[188:189]
	ds_read_b128 v[130:133], v2 offset:20176
	ds_read_b128 v[158:161], v2 offset:21184
	ds_read_b128 v[162:165], v2 offset:21200
	s_waitcnt lgkmcnt(9)
	v_pk_mul_f32 v[134:135], v[96:97], v[134:135]
	v_pk_mul_f32 v[200:201], v[96:97], v[200:201]
	v_pk_fma_f32 v[134:135], v[98:99], v[136:137], v[134:135]
	v_pk_fma_f32 v[200:201], v[98:99], v[202:203], v[200:201]
	v_pk_fma_f32 v[134:135], v[100:101], v[138:139], v[134:135]
	v_pk_fma_f32 v[200:201], v[100:101], v[204:205], v[200:201]
	v_pk_fma_f32 v[134:135], v[102:103], v[140:141], v[134:135]
	v_pk_fma_f32 v[200:201], v[102:103], v[206:207], v[200:201]
	v_add_f32_e32 v136, v134, v135
	v_add_f32_e32 v208, v200, v201
	ds_read_b128 v[174:177], v2 offset:21856
	v_add_f32_dpp v136, v136, v136 quad_perm:[1,0,3,2] row_mask:0xf bank_mask:0xf bound_ctrl:1
	ds_read_b128 v[178:181], v2 offset:21872
	ds_read_b128 v[182:185], v2 offset:22112
	v_add_f32_dpp v136, v136, v136 quad_perm:[2,3,0,1] row_mask:0xf bank_mask:0xf bound_ctrl:1
	ds_read_b128 v[186:189], v2 offset:22128
	ds_read_b128 v[192:195], v2 offset:22368
	v_add_f32_dpp v136, v136, v136 row_half_mirror row_mask:0xf bank_mask:0xf bound_ctrl:1
	s_waitcnt lgkmcnt(12)
	v_pk_mul_f32 v[142:143], v[142:143], v[136:137] op_sel_hi:[1,0]
	v_pk_mul_f32 v[144:145], v[144:145], v[136:137] op_sel_hi:[1,0]
	v_pk_mul_f32 v[146:147], v[146:147], v[136:137] op_sel_hi:[1,0]
	v_pk_mul_f32 v[148:149], v[148:149], v[136:137] op_sel_hi:[1,0]
	ds_read_b128 v[196:199], v2 offset:22384
	s_waitcnt lgkmcnt(10)
	v_pk_fma_f32 v[142:143], v[150:151], v[210:211], v[142:143] op_sel_hi:[1,0,1]
	v_pk_fma_f32 v[144:145], v[152:153], v[210:211], v[144:145] op_sel_hi:[1,0,1]
	v_pk_fma_f32 v[146:147], v[154:155], v[210:211], v[146:147] op_sel_hi:[1,0,1]
	v_pk_fma_f32 v[148:149], v[156:157], v[210:211], v[148:149] op_sel_hi:[1,0,1]
	ds_read_b32 v212, v104 offset:22880
	ds_read_b128 v[166:169], v2 offset:21600
	s_waitcnt lgkmcnt(10)
	v_pk_fma_f32 v[96:97], v[96:97], v[126:127], v[142:143]
	v_pk_fma_f32 v[98:99], v[98:99], v[128:129], v[144:145]
	v_pk_fma_f32 v[100:101], v[100:101], v[130:131], v[146:147]
	v_pk_fma_f32 v[102:103], v[102:103], v[132:133], v[148:149]
	ds_read_b128 v[170:173], v2 offset:21616
	ds_read_b128 v[200:203], v2 offset:22624
	ds_read_b128 v[204:207], v2 offset:22640
	s_waitcnt lgkmcnt(9)
	v_pk_mul_f32 v[174:175], v[96:97], v[174:175]
	v_pk_mul_f32 v[158:159], v[96:97], v[158:159]
	v_pk_fma_f32 v[174:175], v[98:99], v[176:177], v[174:175]
	v_pk_fma_f32 v[158:159], v[98:99], v[160:161], v[158:159]
	v_pk_fma_f32 v[174:175], v[100:101], v[178:179], v[174:175]
	v_pk_fma_f32 v[158:159], v[100:101], v[162:163], v[158:159]
	v_pk_fma_f32 v[174:175], v[102:103], v[180:181], v[174:175]
	v_pk_fma_f32 v[158:159], v[102:103], v[164:165], v[158:159]
	v_add_f32_e32 v176, v174, v175
	v_add_f32_e32 v191, v158, v159
	ds_read_b128 v[134:137], v2 offset:23296
	v_add_f32_dpp v176, v176, v176 quad_perm:[1,0,3,2] row_mask:0xf bank_mask:0xf bound_ctrl:1
	ds_read_b128 v[138:141], v2 offset:23312
	ds_read_b128 v[142:145], v2 offset:23552
	v_add_f32_dpp v176, v176, v176 quad_perm:[2,3,0,1] row_mask:0xf bank_mask:0xf bound_ctrl:1
	ds_read_b128 v[146:149], v2 offset:23568
	ds_read_b128 v[150:153], v2 offset:23808
	v_add_f32_dpp v176, v176, v176 row_half_mirror row_mask:0xf bank_mask:0xf bound_ctrl:1
	s_waitcnt lgkmcnt(12)
	v_pk_mul_f32 v[182:183], v[182:183], v[176:177] op_sel_hi:[1,0]
	v_pk_mul_f32 v[184:185], v[184:185], v[176:177] op_sel_hi:[1,0]
	v_pk_mul_f32 v[186:187], v[186:187], v[176:177] op_sel_hi:[1,0]
	v_pk_mul_f32 v[188:189], v[188:189], v[176:177] op_sel_hi:[1,0]
	ds_read_b128 v[154:157], v2 offset:23824
	s_waitcnt lgkmcnt(10)
	v_pk_fma_f32 v[182:183], v[192:193], v[212:213], v[182:183] op_sel_hi:[1,0,1]
	v_pk_fma_f32 v[184:185], v[194:195], v[212:213], v[184:185] op_sel_hi:[1,0,1]
	v_pk_fma_f32 v[186:187], v[196:197], v[212:213], v[186:187] op_sel_hi:[1,0,1]
	v_pk_fma_f32 v[188:189], v[198:199], v[212:213], v[188:189] op_sel_hi:[1,0,1]
	ds_read_b32 v210, v104 offset:24320
	ds_read_b128 v[126:129], v2 offset:23040
	s_waitcnt lgkmcnt(10)
	v_pk_fma_f32 v[96:97], v[96:97], v[166:167], v[182:183]
	v_pk_fma_f32 v[98:99], v[98:99], v[168:169], v[184:185]
	v_pk_fma_f32 v[100:101], v[100:101], v[170:171], v[186:187]
	v_pk_fma_f32 v[102:103], v[102:103], v[172:173], v[188:189]
	ds_read_b128 v[130:133], v2 offset:23056
	ds_read_b128 v[158:161], v2 offset:24064
	ds_read_b128 v[162:165], v2 offset:24080
	s_waitcnt lgkmcnt(9)
	v_pk_mul_f32 v[134:135], v[96:97], v[134:135]
	v_pk_mul_f32 v[200:201], v[96:97], v[200:201]
	v_pk_fma_f32 v[134:135], v[98:99], v[136:137], v[134:135]
	v_pk_fma_f32 v[200:201], v[98:99], v[202:203], v[200:201]
	v_pk_fma_f32 v[134:135], v[100:101], v[138:139], v[134:135]
	v_pk_fma_f32 v[200:201], v[100:101], v[204:205], v[200:201]
	v_pk_fma_f32 v[134:135], v[102:103], v[140:141], v[134:135]
	v_pk_fma_f32 v[200:201], v[102:103], v[206:207], v[200:201]
	v_add_f32_e32 v136, v134, v135
	v_add_f32_e32 v59, v200, v201
	ds_read_b128 v[174:177], v2 offset:24736
	v_add_f32_dpp v136, v136, v136 quad_perm:[1,0,3,2] row_mask:0xf bank_mask:0xf bound_ctrl:1
	ds_read_b128 v[178:181], v2 offset:24752
	ds_read_b128 v[182:185], v2 offset:24992
	v_add_f32_dpp v136, v136, v136 quad_perm:[2,3,0,1] row_mask:0xf bank_mask:0xf bound_ctrl:1
	ds_read_b128 v[186:189], v2 offset:25008
	ds_read_b128 v[192:195], v2 offset:25248
	v_add_f32_dpp v136, v136, v136 row_half_mirror row_mask:0xf bank_mask:0xf bound_ctrl:1
	v_cndmask_b32_e64 v200, v213, v211, s[10:11]
	v_cndmask_b32_e64 v204, v211, v213, s[10:11]
	v_cndmask_b32_e64 v201, v215, v214, s[10:11]
	v_cndmask_b32_e64 v205, v214, v215, s[10:11]
	v_cndmask_b32_e64 v202, v208, v216, s[10:11]
	v_cndmask_b32_e64 v206, v216, v208, s[10:11]
	v_cndmask_b32_e64 v203, v59, v191, s[10:11]
	v_cndmask_b32_e64 v207, v191, v59, s[10:11]
	v_add_f32_dpp v200, v204, v200 quad_perm:[1,0,3,2] row_mask:0xf bank_mask:0xf bound_ctrl:1
	v_add_f32_dpp v201, v205, v201 quad_perm:[1,0,3,2] row_mask:0xf bank_mask:0xf bound_ctrl:1
	v_add_f32_dpp v202, v206, v202 quad_perm:[1,0,3,2] row_mask:0xf bank_mask:0xf bound_ctrl:1
	v_add_f32_dpp v203, v207, v203 quad_perm:[1,0,3,2] row_mask:0xf bank_mask:0xf bound_ctrl:1
	v_cndmask_b32_e64 v204, v201, v200, s[12:13]
	v_cndmask_b32_e64 v206, v200, v201, s[12:13]
	v_cndmask_b32_e64 v205, v203, v202, s[12:13]
	v_cndmask_b32_e64 v207, v202, v203, s[12:13]
	v_add_f32_dpp v204, v206, v204 quad_perm:[2,3,0,1] row_mask:0xf bank_mask:0xf bound_ctrl:1
	s_nop 0
	v_add_f32_dpp v205, v207, v205 quad_perm:[2,3,0,1] row_mask:0xf bank_mask:0xf bound_ctrl:1
	v_xor_b32_e32 v202, 4, v121
	v_cndmask_b32_e64 v200, v205, v204, s[14:15]
	v_cndmask_b32_e64 v201, v204, v205, s[14:15]
	v_lshlrev_b32_e32 v202, 2, v202
	ds_bpermute_b32 v201, v202, v201
	s_waitcnt lgkmcnt(0)
	v_add_f32_e32 v200, v200, v201
	ds_write_b32 v105, v200 offset:1024
	v_pk_mul_f32 v[142:143], v[142:143], v[136:137] op_sel_hi:[1,0]
	v_pk_mul_f32 v[144:145], v[144:145], v[136:137] op_sel_hi:[1,0]
	v_pk_mul_f32 v[146:147], v[146:147], v[136:137] op_sel_hi:[1,0]
	v_pk_mul_f32 v[148:149], v[148:149], v[136:137] op_sel_hi:[1,0]
	ds_read_b128 v[196:199], v2 offset:25264
	v_pk_fma_f32 v[142:143], v[150:151], v[210:211], v[142:143] op_sel_hi:[1,0,1]
	v_pk_fma_f32 v[144:145], v[152:153], v[210:211], v[144:145] op_sel_hi:[1,0,1]
	v_pk_fma_f32 v[146:147], v[154:155], v[210:211], v[146:147] op_sel_hi:[1,0,1]
	v_pk_fma_f32 v[148:149], v[156:157], v[210:211], v[148:149] op_sel_hi:[1,0,1]
	ds_read_b32 v212, v104 offset:25760
	ds_read_b128 v[166:169], v2 offset:24480
	v_pk_fma_f32 v[96:97], v[96:97], v[126:127], v[142:143]
	v_pk_fma_f32 v[98:99], v[98:99], v[128:129], v[144:145]
	v_pk_fma_f32 v[100:101], v[100:101], v[130:131], v[146:147]
	v_pk_fma_f32 v[102:103], v[102:103], v[132:133], v[148:149]
	ds_read_b128 v[170:173], v2 offset:24496
	ds_read_b128 v[200:203], v2 offset:25504
	ds_read_b128 v[204:207], v2 offset:25520
	v_pk_mul_f32 v[174:175], v[96:97], v[174:175]
	v_pk_mul_f32 v[158:159], v[96:97], v[158:159]
	v_pk_fma_f32 v[174:175], v[98:99], v[176:177], v[174:175]
	v_pk_fma_f32 v[158:159], v[98:99], v[160:161], v[158:159]
	v_pk_fma_f32 v[174:175], v[100:101], v[178:179], v[174:175]
	v_pk_fma_f32 v[158:159], v[100:101], v[162:163], v[158:159]
	v_pk_fma_f32 v[174:175], v[102:103], v[180:181], v[174:175]
	v_pk_fma_f32 v[158:159], v[102:103], v[164:165], v[158:159]
	v_add_f32_e32 v176, v174, v175
	v_add_f32_e32 v211, v158, v159
	ds_read_b128 v[134:137], v2 offset:26176
	v_add_f32_dpp v176, v176, v176 quad_perm:[1,0,3,2] row_mask:0xf bank_mask:0xf bound_ctrl:1
	ds_read_b128 v[138:141], v2 offset:26192
	ds_read_b128 v[142:145], v2 offset:26432
	v_add_f32_dpp v176, v176, v176 quad_perm:[2,3,0,1] row_mask:0xf bank_mask:0xf bound_ctrl:1
	ds_read_b128 v[146:149], v2 offset:26448
	ds_read_b128 v[150:153], v2 offset:26688
	v_add_f32_dpp v176, v176, v176 row_half_mirror row_mask:0xf bank_mask:0xf bound_ctrl:1
	v_pk_mul_f32 v[182:183], v[182:183], v[176:177] op_sel_hi:[1,0]
	v_pk_mul_f32 v[184:185], v[184:185], v[176:177] op_sel_hi:[1,0]
	v_pk_mul_f32 v[186:187], v[186:187], v[176:177] op_sel_hi:[1,0]
	v_pk_mul_f32 v[188:189], v[188:189], v[176:177] op_sel_hi:[1,0]
	ds_read_b128 v[154:157], v2 offset:26704
	s_waitcnt lgkmcnt(10)
	v_pk_fma_f32 v[182:183], v[192:193], v[212:213], v[182:183] op_sel_hi:[1,0,1]
	v_pk_fma_f32 v[184:185], v[194:195], v[212:213], v[184:185] op_sel_hi:[1,0,1]
	v_pk_fma_f32 v[186:187], v[196:197], v[212:213], v[186:187] op_sel_hi:[1,0,1]
	v_pk_fma_f32 v[188:189], v[198:199], v[212:213], v[188:189] op_sel_hi:[1,0,1]
	ds_read_b32 v210, v104 offset:27200
	ds_read_b128 v[126:129], v2 offset:25920
	s_waitcnt lgkmcnt(10)
	v_pk_fma_f32 v[96:97], v[96:97], v[166:167], v[182:183]
	v_pk_fma_f32 v[98:99], v[98:99], v[168:169], v[184:185]
	v_pk_fma_f32 v[100:101], v[100:101], v[170:171], v[186:187]
	v_pk_fma_f32 v[102:103], v[102:103], v[172:173], v[188:189]
	ds_read_b128 v[130:133], v2 offset:25936
	ds_read_b128 v[158:161], v2 offset:26944
	ds_read_b128 v[162:165], v2 offset:26960
	s_waitcnt lgkmcnt(9)
	v_pk_mul_f32 v[134:135], v[96:97], v[134:135]
	v_pk_mul_f32 v[200:201], v[96:97], v[200:201]
	v_pk_fma_f32 v[134:135], v[98:99], v[136:137], v[134:135]
	v_pk_fma_f32 v[200:201], v[98:99], v[202:203], v[200:201]
	v_pk_fma_f32 v[134:135], v[100:101], v[138:139], v[134:135]
	v_pk_fma_f32 v[200:201], v[100:101], v[204:205], v[200:201]
	v_pk_fma_f32 v[134:135], v[102:103], v[140:141], v[134:135]
	v_pk_fma_f32 v[200:201], v[102:103], v[206:207], v[200:201]
	v_add_f32_e32 v136, v134, v135
	v_add_f32_e32 v213, v200, v201
	ds_read_b128 v[174:177], v2 offset:27616
	v_add_f32_dpp v136, v136, v136 quad_perm:[1,0,3,2] row_mask:0xf bank_mask:0xf bound_ctrl:1
	ds_read_b128 v[178:181], v2 offset:27632
	ds_read_b128 v[182:185], v2 offset:27872
	v_add_f32_dpp v136, v136, v136 quad_perm:[2,3,0,1] row_mask:0xf bank_mask:0xf bound_ctrl:1
	ds_read_b128 v[186:189], v2 offset:27888
	ds_read_b128 v[192:195], v2 offset:28128
	v_add_f32_dpp v136, v136, v136 row_half_mirror row_mask:0xf bank_mask:0xf bound_ctrl:1
	s_waitcnt lgkmcnt(12)
	v_pk_mul_f32 v[142:143], v[142:143], v[136:137] op_sel_hi:[1,0]
	v_pk_mul_f32 v[144:145], v[144:145], v[136:137] op_sel_hi:[1,0]
	v_pk_mul_f32 v[146:147], v[146:147], v[136:137] op_sel_hi:[1,0]
	v_pk_mul_f32 v[148:149], v[148:149], v[136:137] op_sel_hi:[1,0]
	ds_read_b128 v[196:199], v2 offset:28144
	s_waitcnt lgkmcnt(10)
	v_pk_fma_f32 v[142:143], v[150:151], v[210:211], v[142:143] op_sel_hi:[1,0,1]
	v_pk_fma_f32 v[144:145], v[152:153], v[210:211], v[144:145] op_sel_hi:[1,0,1]
	v_pk_fma_f32 v[146:147], v[154:155], v[210:211], v[146:147] op_sel_hi:[1,0,1]
	v_pk_fma_f32 v[148:149], v[156:157], v[210:211], v[148:149] op_sel_hi:[1,0,1]
	ds_read_b32 v212, v104 offset:28640
	ds_read_b128 v[166:169], v2 offset:27360
	s_waitcnt lgkmcnt(10)
	v_pk_fma_f32 v[96:97], v[96:97], v[126:127], v[142:143]
	v_pk_fma_f32 v[98:99], v[98:99], v[128:129], v[144:145]
	v_pk_fma_f32 v[100:101], v[100:101], v[130:131], v[146:147]
	v_pk_fma_f32 v[102:103], v[102:103], v[132:133], v[148:149]
	ds_read_b128 v[170:173], v2 offset:27376
	ds_read_b128 v[200:203], v2 offset:28384
	ds_read_b128 v[204:207], v2 offset:28400
	s_waitcnt lgkmcnt(9)
	v_pk_mul_f32 v[174:175], v[96:97], v[174:175]
	v_pk_mul_f32 v[158:159], v[96:97], v[158:159]
	v_pk_fma_f32 v[174:175], v[98:99], v[176:177], v[174:175]
	v_pk_fma_f32 v[158:159], v[98:99], v[160:161], v[158:159]
	v_pk_fma_f32 v[174:175], v[100:101], v[178:179], v[174:175]
	v_pk_fma_f32 v[158:159], v[100:101], v[162:163], v[158:159]
	v_pk_fma_f32 v[174:175], v[102:103], v[180:181], v[174:175]
	v_pk_fma_f32 v[158:159], v[102:103], v[164:165], v[158:159]
	v_add_f32_e32 v176, v174, v175
	v_add_f32_e32 v214, v158, v159
	ds_read_b128 v[134:137], v2 offset:29056
	v_add_f32_dpp v176, v176, v176 quad_perm:[1,0,3,2] row_mask:0xf bank_mask:0xf bound_ctrl:1
	ds_read_b128 v[138:141], v2 offset:29072
	ds_read_b128 v[142:145], v2 offset:29312
	v_add_f32_dpp v176, v176, v176 quad_perm:[2,3,0,1] row_mask:0xf bank_mask:0xf bound_ctrl:1
	ds_read_b128 v[146:149], v2 offset:29328
	ds_read_b128 v[150:153], v2 offset:29568
	v_add_f32_dpp v176, v176, v176 row_half_mirror row_mask:0xf bank_mask:0xf bound_ctrl:1
	s_waitcnt lgkmcnt(12)
	v_pk_mul_f32 v[182:183], v[182:183], v[176:177] op_sel_hi:[1,0]
	v_pk_mul_f32 v[184:185], v[184:185], v[176:177] op_sel_hi:[1,0]
	v_pk_mul_f32 v[186:187], v[186:187], v[176:177] op_sel_hi:[1,0]
	v_pk_mul_f32 v[188:189], v[188:189], v[176:177] op_sel_hi:[1,0]
	ds_read_b128 v[154:157], v2 offset:29584
	s_waitcnt lgkmcnt(10)
	v_pk_fma_f32 v[182:183], v[192:193], v[212:213], v[182:183] op_sel_hi:[1,0,1]
	v_pk_fma_f32 v[184:185], v[194:195], v[212:213], v[184:185] op_sel_hi:[1,0,1]
	v_pk_fma_f32 v[186:187], v[196:197], v[212:213], v[186:187] op_sel_hi:[1,0,1]
	v_pk_fma_f32 v[188:189], v[198:199], v[212:213], v[188:189] op_sel_hi:[1,0,1]
	ds_read_b32 v210, v104 offset:30080
	ds_read_b128 v[126:129], v2 offset:28800
	s_waitcnt lgkmcnt(10)
	v_pk_fma_f32 v[96:97], v[96:97], v[166:167], v[182:183]
	v_pk_fma_f32 v[98:99], v[98:99], v[168:169], v[184:185]
	v_pk_fma_f32 v[100:101], v[100:101], v[170:171], v[186:187]
	v_pk_fma_f32 v[102:103], v[102:103], v[172:173], v[188:189]
	ds_read_b128 v[130:133], v2 offset:28816
	ds_read_b128 v[158:161], v2 offset:29824
	ds_read_b128 v[162:165], v2 offset:29840
	s_waitcnt lgkmcnt(9)
	v_pk_mul_f32 v[134:135], v[96:97], v[134:135]
	v_pk_mul_f32 v[200:201], v[96:97], v[200:201]
	v_pk_fma_f32 v[134:135], v[98:99], v[136:137], v[134:135]
	v_pk_fma_f32 v[200:201], v[98:99], v[202:203], v[200:201]
	v_pk_fma_f32 v[134:135], v[100:101], v[138:139], v[134:135]
	v_pk_fma_f32 v[200:201], v[100:101], v[204:205], v[200:201]
	v_pk_fma_f32 v[134:135], v[102:103], v[140:141], v[134:135]
	v_pk_fma_f32 v[200:201], v[102:103], v[206:207], v[200:201]
	v_add_f32_e32 v136, v134, v135
	v_add_f32_e32 v215, v200, v201
	ds_read_b128 v[174:177], v2 offset:30496
	v_add_f32_dpp v136, v136, v136 quad_perm:[1,0,3,2] row_mask:0xf bank_mask:0xf bound_ctrl:1
	ds_read_b128 v[178:181], v2 offset:30512
	ds_read_b128 v[182:185], v2 offset:30752
	v_add_f32_dpp v136, v136, v136 quad_perm:[2,3,0,1] row_mask:0xf bank_mask:0xf bound_ctrl:1
	ds_read_b128 v[186:189], v2 offset:30768
	ds_read_b128 v[192:195], v2 offset:31008
	v_add_f32_dpp v136, v136, v136 row_half_mirror row_mask:0xf bank_mask:0xf bound_ctrl:1
	s_waitcnt lgkmcnt(12)
	v_pk_mul_f32 v[142:143], v[142:143], v[136:137] op_sel_hi:[1,0]
	v_pk_mul_f32 v[144:145], v[144:145], v[136:137] op_sel_hi:[1,0]
	v_pk_mul_f32 v[146:147], v[146:147], v[136:137] op_sel_hi:[1,0]
	v_pk_mul_f32 v[148:149], v[148:149], v[136:137] op_sel_hi:[1,0]
	ds_read_b128 v[196:199], v2 offset:31024
	s_waitcnt lgkmcnt(10)
	v_pk_fma_f32 v[142:143], v[150:151], v[210:211], v[142:143] op_sel_hi:[1,0,1]
	v_pk_fma_f32 v[144:145], v[152:153], v[210:211], v[144:145] op_sel_hi:[1,0,1]
	v_pk_fma_f32 v[146:147], v[154:155], v[210:211], v[146:147] op_sel_hi:[1,0,1]
	v_pk_fma_f32 v[148:149], v[156:157], v[210:211], v[148:149] op_sel_hi:[1,0,1]
	ds_read_b32 v212, v104 offset:31520
	ds_read_b128 v[166:169], v2 offset:30240
	s_waitcnt lgkmcnt(10)
	v_pk_fma_f32 v[96:97], v[96:97], v[126:127], v[142:143]
	v_pk_fma_f32 v[98:99], v[98:99], v[128:129], v[144:145]
	v_pk_fma_f32 v[100:101], v[100:101], v[130:131], v[146:147]
	v_pk_fma_f32 v[102:103], v[102:103], v[132:133], v[148:149]
	ds_read_b128 v[170:173], v2 offset:30256
	ds_read_b128 v[200:203], v2 offset:31264
	ds_read_b128 v[204:207], v2 offset:31280
	s_waitcnt lgkmcnt(9)
	v_pk_mul_f32 v[174:175], v[96:97], v[174:175]
	v_pk_mul_f32 v[158:159], v[96:97], v[158:159]
	v_pk_fma_f32 v[174:175], v[98:99], v[176:177], v[174:175]
	v_pk_fma_f32 v[158:159], v[98:99], v[160:161], v[158:159]
	v_pk_fma_f32 v[174:175], v[100:101], v[178:179], v[174:175]
	v_pk_fma_f32 v[158:159], v[100:101], v[162:163], v[158:159]
	v_pk_fma_f32 v[174:175], v[102:103], v[180:181], v[174:175]
	v_pk_fma_f32 v[158:159], v[102:103], v[164:165], v[158:159]
	v_add_f32_e32 v176, v174, v175
	v_add_f32_e32 v216, v158, v159
	ds_read_b128 v[134:137], v2 offset:31936
	v_add_f32_dpp v176, v176, v176 quad_perm:[1,0,3,2] row_mask:0xf bank_mask:0xf bound_ctrl:1
	ds_read_b128 v[138:141], v2 offset:31952
	ds_read_b128 v[142:145], v2 offset:32192
	v_add_f32_dpp v176, v176, v176 quad_perm:[2,3,0,1] row_mask:0xf bank_mask:0xf bound_ctrl:1
	ds_read_b128 v[146:149], v2 offset:32208
	ds_read_b128 v[150:153], v2 offset:32448
	v_add_f32_dpp v176, v176, v176 row_half_mirror row_mask:0xf bank_mask:0xf bound_ctrl:1
	s_waitcnt lgkmcnt(12)
	v_pk_mul_f32 v[182:183], v[182:183], v[176:177] op_sel_hi:[1,0]
	v_pk_mul_f32 v[184:185], v[184:185], v[176:177] op_sel_hi:[1,0]
	v_pk_mul_f32 v[186:187], v[186:187], v[176:177] op_sel_hi:[1,0]
	v_pk_mul_f32 v[188:189], v[188:189], v[176:177] op_sel_hi:[1,0]
	ds_read_b128 v[154:157], v2 offset:32464
	s_waitcnt lgkmcnt(10)
	v_pk_fma_f32 v[182:183], v[192:193], v[212:213], v[182:183] op_sel_hi:[1,0,1]
	v_pk_fma_f32 v[184:185], v[194:195], v[212:213], v[184:185] op_sel_hi:[1,0,1]
	v_pk_fma_f32 v[186:187], v[196:197], v[212:213], v[186:187] op_sel_hi:[1,0,1]
	v_pk_fma_f32 v[188:189], v[198:199], v[212:213], v[188:189] op_sel_hi:[1,0,1]
	ds_read_b32 v210, v104 offset:32960
	ds_read_b128 v[126:129], v2 offset:31680
	s_waitcnt lgkmcnt(10)
	v_pk_fma_f32 v[96:97], v[96:97], v[166:167], v[182:183]
	v_pk_fma_f32 v[98:99], v[98:99], v[168:169], v[184:185]
	v_pk_fma_f32 v[100:101], v[100:101], v[170:171], v[186:187]
	v_pk_fma_f32 v[102:103], v[102:103], v[172:173], v[188:189]
	ds_read_b128 v[130:133], v2 offset:31696
	ds_read_b128 v[158:161], v2 offset:32704
	ds_read_b128 v[162:165], v2 offset:32720
	s_waitcnt lgkmcnt(9)
	v_pk_mul_f32 v[134:135], v[96:97], v[134:135]
	v_pk_mul_f32 v[200:201], v[96:97], v[200:201]
	v_pk_fma_f32 v[134:135], v[98:99], v[136:137], v[134:135]
	v_pk_fma_f32 v[200:201], v[98:99], v[202:203], v[200:201]
	v_pk_fma_f32 v[134:135], v[100:101], v[138:139], v[134:135]
	v_pk_fma_f32 v[200:201], v[100:101], v[204:205], v[200:201]
	v_pk_fma_f32 v[134:135], v[102:103], v[140:141], v[134:135]
	v_pk_fma_f32 v[200:201], v[102:103], v[206:207], v[200:201]
	v_add_f32_e32 v136, v134, v135
	v_add_f32_e32 v208, v200, v201
	ds_read_b128 v[174:177], v2 offset:33376
	v_add_f32_dpp v136, v136, v136 quad_perm:[1,0,3,2] row_mask:0xf bank_mask:0xf bound_ctrl:1
	ds_read_b128 v[178:181], v2 offset:33392
	ds_read_b128 v[182:185], v2 offset:33632
	v_add_f32_dpp v136, v136, v136 quad_perm:[2,3,0,1] row_mask:0xf bank_mask:0xf bound_ctrl:1
	ds_read_b128 v[186:189], v2 offset:33648
	ds_read_b128 v[192:195], v2 offset:33888
	v_add_f32_dpp v136, v136, v136 row_half_mirror row_mask:0xf bank_mask:0xf bound_ctrl:1
	s_waitcnt lgkmcnt(12)
	v_pk_mul_f32 v[142:143], v[142:143], v[136:137] op_sel_hi:[1,0]
	v_pk_mul_f32 v[144:145], v[144:145], v[136:137] op_sel_hi:[1,0]
	v_pk_mul_f32 v[146:147], v[146:147], v[136:137] op_sel_hi:[1,0]
	v_pk_mul_f32 v[148:149], v[148:149], v[136:137] op_sel_hi:[1,0]
	ds_read_b128 v[196:199], v2 offset:33904
	s_waitcnt lgkmcnt(10)
	v_pk_fma_f32 v[142:143], v[150:151], v[210:211], v[142:143] op_sel_hi:[1,0,1]
	v_pk_fma_f32 v[144:145], v[152:153], v[210:211], v[144:145] op_sel_hi:[1,0,1]
	v_pk_fma_f32 v[146:147], v[154:155], v[210:211], v[146:147] op_sel_hi:[1,0,1]
	v_pk_fma_f32 v[148:149], v[156:157], v[210:211], v[148:149] op_sel_hi:[1,0,1]
	ds_read_b32 v212, v104 offset:34400
	ds_read_b128 v[166:169], v2 offset:33120
	s_waitcnt lgkmcnt(10)
	v_pk_fma_f32 v[96:97], v[96:97], v[126:127], v[142:143]
	v_pk_fma_f32 v[98:99], v[98:99], v[128:129], v[144:145]
	v_pk_fma_f32 v[100:101], v[100:101], v[130:131], v[146:147]
	v_pk_fma_f32 v[102:103], v[102:103], v[132:133], v[148:149]
	ds_read_b128 v[170:173], v2 offset:33136
	ds_read_b128 v[200:203], v2 offset:34144
	ds_read_b128 v[204:207], v2 offset:34160
	s_waitcnt lgkmcnt(9)
	v_pk_mul_f32 v[174:175], v[96:97], v[174:175]
	v_pk_mul_f32 v[158:159], v[96:97], v[158:159]
	v_pk_fma_f32 v[174:175], v[98:99], v[176:177], v[174:175]
	v_pk_fma_f32 v[158:159], v[98:99], v[160:161], v[158:159]
	v_pk_fma_f32 v[174:175], v[100:101], v[178:179], v[174:175]
	v_pk_fma_f32 v[158:159], v[100:101], v[162:163], v[158:159]
	v_pk_fma_f32 v[174:175], v[102:103], v[180:181], v[174:175]
	v_pk_fma_f32 v[158:159], v[102:103], v[164:165], v[158:159]
	v_add_f32_e32 v176, v174, v175
	v_add_f32_e32 v191, v158, v159
	ds_read_b128 v[134:137], v2 offset:34816
	v_add_f32_dpp v176, v176, v176 quad_perm:[1,0,3,2] row_mask:0xf bank_mask:0xf bound_ctrl:1
	ds_read_b128 v[138:141], v2 offset:34832
	ds_read_b128 v[142:145], v2 offset:35072
	v_add_f32_dpp v176, v176, v176 quad_perm:[2,3,0,1] row_mask:0xf bank_mask:0xf bound_ctrl:1
	ds_read_b128 v[146:149], v2 offset:35088
	ds_read_b128 v[150:153], v2 offset:35328
	v_add_f32_dpp v176, v176, v176 row_half_mirror row_mask:0xf bank_mask:0xf bound_ctrl:1
	s_waitcnt lgkmcnt(12)
	v_pk_mul_f32 v[182:183], v[182:183], v[176:177] op_sel_hi:[1,0]
	v_pk_mul_f32 v[184:185], v[184:185], v[176:177] op_sel_hi:[1,0]
	v_pk_mul_f32 v[186:187], v[186:187], v[176:177] op_sel_hi:[1,0]
	v_pk_mul_f32 v[188:189], v[188:189], v[176:177] op_sel_hi:[1,0]
	ds_read_b128 v[154:157], v2 offset:35344
	s_waitcnt lgkmcnt(10)
	v_pk_fma_f32 v[182:183], v[192:193], v[212:213], v[182:183] op_sel_hi:[1,0,1]
	v_pk_fma_f32 v[184:185], v[194:195], v[212:213], v[184:185] op_sel_hi:[1,0,1]
	v_pk_fma_f32 v[186:187], v[196:197], v[212:213], v[186:187] op_sel_hi:[1,0,1]
	v_pk_fma_f32 v[188:189], v[198:199], v[212:213], v[188:189] op_sel_hi:[1,0,1]
	ds_read_b32 v210, v104 offset:35840
	ds_read_b128 v[126:129], v2 offset:34560
	s_waitcnt lgkmcnt(10)
	v_pk_fma_f32 v[96:97], v[96:97], v[166:167], v[182:183]
	v_pk_fma_f32 v[98:99], v[98:99], v[168:169], v[184:185]
	v_pk_fma_f32 v[100:101], v[100:101], v[170:171], v[186:187]
	v_pk_fma_f32 v[102:103], v[102:103], v[172:173], v[188:189]
	ds_read_b128 v[130:133], v2 offset:34576
	ds_read_b128 v[158:161], v2 offset:35584
	ds_read_b128 v[162:165], v2 offset:35600
	s_waitcnt lgkmcnt(9)
	v_pk_mul_f32 v[134:135], v[96:97], v[134:135]
	v_pk_mul_f32 v[200:201], v[96:97], v[200:201]
	v_pk_fma_f32 v[134:135], v[98:99], v[136:137], v[134:135]
	v_pk_fma_f32 v[200:201], v[98:99], v[202:203], v[200:201]
	v_pk_fma_f32 v[134:135], v[100:101], v[138:139], v[134:135]
	v_pk_fma_f32 v[200:201], v[100:101], v[204:205], v[200:201]
	v_pk_fma_f32 v[134:135], v[102:103], v[140:141], v[134:135]
	v_pk_fma_f32 v[200:201], v[102:103], v[206:207], v[200:201]
	v_add_f32_e32 v136, v134, v135
	v_add_f32_e32 v59, v200, v201
	ds_read_b128 v[174:177], v2 offset:36256
	v_add_f32_dpp v136, v136, v136 quad_perm:[1,0,3,2] row_mask:0xf bank_mask:0xf bound_ctrl:1
	ds_read_b128 v[178:181], v2 offset:36272
	ds_read_b128 v[182:185], v2 offset:36512
	v_add_f32_dpp v136, v136, v136 quad_perm:[2,3,0,1] row_mask:0xf bank_mask:0xf bound_ctrl:1
	ds_read_b128 v[186:189], v2 offset:36528
	ds_read_b128 v[192:195], v2 offset:36768
	v_add_f32_dpp v136, v136, v136 row_half_mirror row_mask:0xf bank_mask:0xf bound_ctrl:1
	v_cndmask_b32_e64 v200, v213, v211, s[10:11]
	v_cndmask_b32_e64 v204, v211, v213, s[10:11]
	v_cndmask_b32_e64 v201, v215, v214, s[10:11]
	v_cndmask_b32_e64 v205, v214, v215, s[10:11]
	v_cndmask_b32_e64 v202, v208, v216, s[10:11]
	v_cndmask_b32_e64 v206, v216, v208, s[10:11]
	v_cndmask_b32_e64 v203, v59, v191, s[10:11]
	v_cndmask_b32_e64 v207, v191, v59, s[10:11]
	v_add_f32_dpp v200, v204, v200 quad_perm:[1,0,3,2] row_mask:0xf bank_mask:0xf bound_ctrl:1
	v_add_f32_dpp v201, v205, v201 quad_perm:[1,0,3,2] row_mask:0xf bank_mask:0xf bound_ctrl:1
	v_add_f32_dpp v202, v206, v202 quad_perm:[1,0,3,2] row_mask:0xf bank_mask:0xf bound_ctrl:1
	v_add_f32_dpp v203, v207, v203 quad_perm:[1,0,3,2] row_mask:0xf bank_mask:0xf bound_ctrl:1
	v_cndmask_b32_e64 v204, v201, v200, s[12:13]
	v_cndmask_b32_e64 v206, v200, v201, s[12:13]
	v_cndmask_b32_e64 v205, v203, v202, s[12:13]
	v_cndmask_b32_e64 v207, v202, v203, s[12:13]
	v_add_f32_dpp v204, v206, v204 quad_perm:[2,3,0,1] row_mask:0xf bank_mask:0xf bound_ctrl:1
	s_nop 0
	v_add_f32_dpp v205, v207, v205 quad_perm:[2,3,0,1] row_mask:0xf bank_mask:0xf bound_ctrl:1
	v_xor_b32_e32 v202, 4, v121
	v_cndmask_b32_e64 v200, v205, v204, s[14:15]
	v_cndmask_b32_e64 v201, v204, v205, s[14:15]
	v_lshlrev_b32_e32 v202, 2, v202
	ds_bpermute_b32 v201, v202, v201
	s_waitcnt lgkmcnt(0)
	v_add_f32_e32 v200, v200, v201
	ds_write_b32 v105, v200 offset:2048
	v_pk_mul_f32 v[142:143], v[142:143], v[136:137] op_sel_hi:[1,0]
	v_pk_mul_f32 v[144:145], v[144:145], v[136:137] op_sel_hi:[1,0]
	v_pk_mul_f32 v[146:147], v[146:147], v[136:137] op_sel_hi:[1,0]
	v_pk_mul_f32 v[148:149], v[148:149], v[136:137] op_sel_hi:[1,0]
	ds_read_b128 v[196:199], v2 offset:36784
	v_pk_fma_f32 v[142:143], v[150:151], v[210:211], v[142:143] op_sel_hi:[1,0,1]
	v_pk_fma_f32 v[144:145], v[152:153], v[210:211], v[144:145] op_sel_hi:[1,0,1]
	v_pk_fma_f32 v[146:147], v[154:155], v[210:211], v[146:147] op_sel_hi:[1,0,1]
	v_pk_fma_f32 v[148:149], v[156:157], v[210:211], v[148:149] op_sel_hi:[1,0,1]
	ds_read_b32 v212, v104 offset:37280
	ds_read_b128 v[166:169], v2 offset:36000
	v_pk_fma_f32 v[96:97], v[96:97], v[126:127], v[142:143]
	v_pk_fma_f32 v[98:99], v[98:99], v[128:129], v[144:145]
	v_pk_fma_f32 v[100:101], v[100:101], v[130:131], v[146:147]
	v_pk_fma_f32 v[102:103], v[102:103], v[132:133], v[148:149]
	ds_read_b128 v[170:173], v2 offset:36016
	ds_read_b128 v[200:203], v2 offset:37024
	ds_read_b128 v[204:207], v2 offset:37040
	v_pk_mul_f32 v[174:175], v[96:97], v[174:175]
	v_pk_mul_f32 v[158:159], v[96:97], v[158:159]
	v_pk_fma_f32 v[174:175], v[98:99], v[176:177], v[174:175]
	v_pk_fma_f32 v[158:159], v[98:99], v[160:161], v[158:159]
	v_pk_fma_f32 v[174:175], v[100:101], v[178:179], v[174:175]
	v_pk_fma_f32 v[158:159], v[100:101], v[162:163], v[158:159]
	v_pk_fma_f32 v[174:175], v[102:103], v[180:181], v[174:175]
	v_pk_fma_f32 v[158:159], v[102:103], v[164:165], v[158:159]
	v_add_f32_e32 v176, v174, v175
	v_add_f32_e32 v211, v158, v159
	ds_read_b128 v[134:137], v2 offset:37696
	v_add_f32_dpp v176, v176, v176 quad_perm:[1,0,3,2] row_mask:0xf bank_mask:0xf bound_ctrl:1
	ds_read_b128 v[138:141], v2 offset:37712
	ds_read_b128 v[142:145], v2 offset:37952
	v_add_f32_dpp v176, v176, v176 quad_perm:[2,3,0,1] row_mask:0xf bank_mask:0xf bound_ctrl:1
	ds_read_b128 v[146:149], v2 offset:37968
	ds_read_b128 v[150:153], v2 offset:38208
	v_add_f32_dpp v176, v176, v176 row_half_mirror row_mask:0xf bank_mask:0xf bound_ctrl:1
	v_pk_mul_f32 v[182:183], v[182:183], v[176:177] op_sel_hi:[1,0]
	v_pk_mul_f32 v[184:185], v[184:185], v[176:177] op_sel_hi:[1,0]
	v_pk_mul_f32 v[186:187], v[186:187], v[176:177] op_sel_hi:[1,0]
	v_pk_mul_f32 v[188:189], v[188:189], v[176:177] op_sel_hi:[1,0]
	ds_read_b128 v[154:157], v2 offset:38224
	s_waitcnt lgkmcnt(10)
	v_pk_fma_f32 v[182:183], v[192:193], v[212:213], v[182:183] op_sel_hi:[1,0,1]
	v_pk_fma_f32 v[184:185], v[194:195], v[212:213], v[184:185] op_sel_hi:[1,0,1]
	v_pk_fma_f32 v[186:187], v[196:197], v[212:213], v[186:187] op_sel_hi:[1,0,1]
	v_pk_fma_f32 v[188:189], v[198:199], v[212:213], v[188:189] op_sel_hi:[1,0,1]
	ds_read_b32 v210, v104 offset:38720
	ds_read_b128 v[126:129], v2 offset:37440
	s_waitcnt lgkmcnt(10)
	v_pk_fma_f32 v[96:97], v[96:97], v[166:167], v[182:183]
	v_pk_fma_f32 v[98:99], v[98:99], v[168:169], v[184:185]
	v_pk_fma_f32 v[100:101], v[100:101], v[170:171], v[186:187]
	v_pk_fma_f32 v[102:103], v[102:103], v[172:173], v[188:189]
	ds_read_b128 v[130:133], v2 offset:37456
	ds_read_b128 v[158:161], v2 offset:38464
	ds_read_b128 v[162:165], v2 offset:38480
	s_waitcnt lgkmcnt(9)
	v_pk_mul_f32 v[134:135], v[96:97], v[134:135]
	v_pk_mul_f32 v[200:201], v[96:97], v[200:201]
	v_pk_fma_f32 v[134:135], v[98:99], v[136:137], v[134:135]
	v_pk_fma_f32 v[200:201], v[98:99], v[202:203], v[200:201]
	v_pk_fma_f32 v[134:135], v[100:101], v[138:139], v[134:135]
	v_pk_fma_f32 v[200:201], v[100:101], v[204:205], v[200:201]
	v_pk_fma_f32 v[134:135], v[102:103], v[140:141], v[134:135]
	v_pk_fma_f32 v[200:201], v[102:103], v[206:207], v[200:201]
	v_add_f32_e32 v136, v134, v135
	v_add_f32_e32 v213, v200, v201
	ds_read_b128 v[174:177], v2 offset:39136
	v_add_f32_dpp v136, v136, v136 quad_perm:[1,0,3,2] row_mask:0xf bank_mask:0xf bound_ctrl:1
	ds_read_b128 v[178:181], v2 offset:39152
	ds_read_b128 v[182:185], v2 offset:39392
	v_add_f32_dpp v136, v136, v136 quad_perm:[2,3,0,1] row_mask:0xf bank_mask:0xf bound_ctrl:1
	ds_read_b128 v[186:189], v2 offset:39408
	ds_read_b128 v[192:195], v2 offset:39648
	v_add_f32_dpp v136, v136, v136 row_half_mirror row_mask:0xf bank_mask:0xf bound_ctrl:1
	s_waitcnt lgkmcnt(12)
	v_pk_mul_f32 v[142:143], v[142:143], v[136:137] op_sel_hi:[1,0]
	v_pk_mul_f32 v[144:145], v[144:145], v[136:137] op_sel_hi:[1,0]
	v_pk_mul_f32 v[146:147], v[146:147], v[136:137] op_sel_hi:[1,0]
	v_pk_mul_f32 v[148:149], v[148:149], v[136:137] op_sel_hi:[1,0]
	ds_read_b128 v[196:199], v2 offset:39664
	s_waitcnt lgkmcnt(10)
	v_pk_fma_f32 v[142:143], v[150:151], v[210:211], v[142:143] op_sel_hi:[1,0,1]
	v_pk_fma_f32 v[144:145], v[152:153], v[210:211], v[144:145] op_sel_hi:[1,0,1]
	v_pk_fma_f32 v[146:147], v[154:155], v[210:211], v[146:147] op_sel_hi:[1,0,1]
	v_pk_fma_f32 v[148:149], v[156:157], v[210:211], v[148:149] op_sel_hi:[1,0,1]
	ds_read_b32 v212, v104 offset:40160
	ds_read_b128 v[166:169], v2 offset:38880
	s_waitcnt lgkmcnt(10)
	v_pk_fma_f32 v[96:97], v[96:97], v[126:127], v[142:143]
	v_pk_fma_f32 v[98:99], v[98:99], v[128:129], v[144:145]
	v_pk_fma_f32 v[100:101], v[100:101], v[130:131], v[146:147]
	v_pk_fma_f32 v[102:103], v[102:103], v[132:133], v[148:149]
	ds_read_b128 v[170:173], v2 offset:38896
	ds_read_b128 v[200:203], v2 offset:39904
	ds_read_b128 v[204:207], v2 offset:39920
	s_waitcnt lgkmcnt(9)
	v_pk_mul_f32 v[174:175], v[96:97], v[174:175]
	v_pk_mul_f32 v[158:159], v[96:97], v[158:159]
	v_pk_fma_f32 v[174:175], v[98:99], v[176:177], v[174:175]
	v_pk_fma_f32 v[158:159], v[98:99], v[160:161], v[158:159]
	v_pk_fma_f32 v[174:175], v[100:101], v[178:179], v[174:175]
	v_pk_fma_f32 v[158:159], v[100:101], v[162:163], v[158:159]
	v_pk_fma_f32 v[174:175], v[102:103], v[180:181], v[174:175]
	v_pk_fma_f32 v[158:159], v[102:103], v[164:165], v[158:159]
	v_add_f32_e32 v176, v174, v175
	v_add_f32_e32 v214, v158, v159
	ds_read_b128 v[134:137], v2 offset:40576
	v_add_f32_dpp v176, v176, v176 quad_perm:[1,0,3,2] row_mask:0xf bank_mask:0xf bound_ctrl:1
	ds_read_b128 v[138:141], v2 offset:40592
	ds_read_b128 v[142:145], v2 offset:40832
	v_add_f32_dpp v176, v176, v176 quad_perm:[2,3,0,1] row_mask:0xf bank_mask:0xf bound_ctrl:1
	ds_read_b128 v[146:149], v2 offset:40848
	ds_read_b128 v[150:153], v2 offset:41088
	v_add_f32_dpp v176, v176, v176 row_half_mirror row_mask:0xf bank_mask:0xf bound_ctrl:1
	s_waitcnt lgkmcnt(12)
	v_pk_mul_f32 v[182:183], v[182:183], v[176:177] op_sel_hi:[1,0]
	v_pk_mul_f32 v[184:185], v[184:185], v[176:177] op_sel_hi:[1,0]
	v_pk_mul_f32 v[186:187], v[186:187], v[176:177] op_sel_hi:[1,0]
	v_pk_mul_f32 v[188:189], v[188:189], v[176:177] op_sel_hi:[1,0]
	ds_read_b128 v[154:157], v2 offset:41104
	s_waitcnt lgkmcnt(10)
	v_pk_fma_f32 v[182:183], v[192:193], v[212:213], v[182:183] op_sel_hi:[1,0,1]
	v_pk_fma_f32 v[184:185], v[194:195], v[212:213], v[184:185] op_sel_hi:[1,0,1]
	v_pk_fma_f32 v[186:187], v[196:197], v[212:213], v[186:187] op_sel_hi:[1,0,1]
	v_pk_fma_f32 v[188:189], v[198:199], v[212:213], v[188:189] op_sel_hi:[1,0,1]
	ds_read_b32 v210, v104 offset:41600
	ds_read_b128 v[126:129], v2 offset:40320
	s_waitcnt lgkmcnt(10)
	v_pk_fma_f32 v[96:97], v[96:97], v[166:167], v[182:183]
	v_pk_fma_f32 v[98:99], v[98:99], v[168:169], v[184:185]
	v_pk_fma_f32 v[100:101], v[100:101], v[170:171], v[186:187]
	v_pk_fma_f32 v[102:103], v[102:103], v[172:173], v[188:189]
	ds_read_b128 v[130:133], v2 offset:40336
	ds_read_b128 v[158:161], v2 offset:41344
	ds_read_b128 v[162:165], v2 offset:41360
	s_waitcnt lgkmcnt(9)
	v_pk_mul_f32 v[134:135], v[96:97], v[134:135]
	v_pk_mul_f32 v[200:201], v[96:97], v[200:201]
	v_pk_fma_f32 v[134:135], v[98:99], v[136:137], v[134:135]
	v_pk_fma_f32 v[200:201], v[98:99], v[202:203], v[200:201]
	v_pk_fma_f32 v[134:135], v[100:101], v[138:139], v[134:135]
	v_pk_fma_f32 v[200:201], v[100:101], v[204:205], v[200:201]
	v_pk_fma_f32 v[134:135], v[102:103], v[140:141], v[134:135]
	v_pk_fma_f32 v[200:201], v[102:103], v[206:207], v[200:201]
	v_add_f32_e32 v136, v134, v135
	v_add_f32_e32 v215, v200, v201
	ds_read_b128 v[174:177], v2 offset:42016
	v_add_f32_dpp v136, v136, v136 quad_perm:[1,0,3,2] row_mask:0xf bank_mask:0xf bound_ctrl:1
	ds_read_b128 v[178:181], v2 offset:42032
	ds_read_b128 v[182:185], v2 offset:42272
	v_add_f32_dpp v136, v136, v136 quad_perm:[2,3,0,1] row_mask:0xf bank_mask:0xf bound_ctrl:1
	ds_read_b128 v[186:189], v2 offset:42288
	ds_read_b128 v[192:195], v2 offset:42528
	v_add_f32_dpp v136, v136, v136 row_half_mirror row_mask:0xf bank_mask:0xf bound_ctrl:1
	s_waitcnt lgkmcnt(12)
	v_pk_mul_f32 v[142:143], v[142:143], v[136:137] op_sel_hi:[1,0]
	v_pk_mul_f32 v[144:145], v[144:145], v[136:137] op_sel_hi:[1,0]
	v_pk_mul_f32 v[146:147], v[146:147], v[136:137] op_sel_hi:[1,0]
	v_pk_mul_f32 v[148:149], v[148:149], v[136:137] op_sel_hi:[1,0]
	ds_read_b128 v[196:199], v2 offset:42544
	s_waitcnt lgkmcnt(10)
	v_pk_fma_f32 v[142:143], v[150:151], v[210:211], v[142:143] op_sel_hi:[1,0,1]
	v_pk_fma_f32 v[144:145], v[152:153], v[210:211], v[144:145] op_sel_hi:[1,0,1]
	v_pk_fma_f32 v[146:147], v[154:155], v[210:211], v[146:147] op_sel_hi:[1,0,1]
	v_pk_fma_f32 v[148:149], v[156:157], v[210:211], v[148:149] op_sel_hi:[1,0,1]
	ds_read_b32 v212, v104 offset:43040
	ds_read_b128 v[166:169], v2 offset:41760
	s_waitcnt lgkmcnt(10)
	v_pk_fma_f32 v[96:97], v[96:97], v[126:127], v[142:143]
	v_pk_fma_f32 v[98:99], v[98:99], v[128:129], v[144:145]
	v_pk_fma_f32 v[100:101], v[100:101], v[130:131], v[146:147]
	v_pk_fma_f32 v[102:103], v[102:103], v[132:133], v[148:149]
	ds_read_b128 v[170:173], v2 offset:41776
	ds_read_b128 v[200:203], v2 offset:42784
	ds_read_b128 v[204:207], v2 offset:42800
	s_waitcnt lgkmcnt(9)
	v_pk_mul_f32 v[174:175], v[96:97], v[174:175]
	v_pk_mul_f32 v[158:159], v[96:97], v[158:159]
	v_pk_fma_f32 v[174:175], v[98:99], v[176:177], v[174:175]
	v_pk_fma_f32 v[158:159], v[98:99], v[160:161], v[158:159]
	v_pk_fma_f32 v[174:175], v[100:101], v[178:179], v[174:175]
	v_pk_fma_f32 v[158:159], v[100:101], v[162:163], v[158:159]
	v_pk_fma_f32 v[174:175], v[102:103], v[180:181], v[174:175]
	v_pk_fma_f32 v[158:159], v[102:103], v[164:165], v[158:159]
	v_add_f32_e32 v176, v174, v175
	v_add_f32_e32 v216, v158, v159
	ds_read_b128 v[134:137], v2 offset:43456
	v_add_f32_dpp v176, v176, v176 quad_perm:[1,0,3,2] row_mask:0xf bank_mask:0xf bound_ctrl:1
	ds_read_b128 v[138:141], v2 offset:43472
	ds_read_b128 v[142:145], v2 offset:43712
	v_add_f32_dpp v176, v176, v176 quad_perm:[2,3,0,1] row_mask:0xf bank_mask:0xf bound_ctrl:1
	ds_read_b128 v[146:149], v2 offset:43728
	ds_read_b128 v[150:153], v2 offset:43968
	v_add_f32_dpp v176, v176, v176 row_half_mirror row_mask:0xf bank_mask:0xf bound_ctrl:1
	s_waitcnt lgkmcnt(12)
	v_pk_mul_f32 v[182:183], v[182:183], v[176:177] op_sel_hi:[1,0]
	v_pk_mul_f32 v[184:185], v[184:185], v[176:177] op_sel_hi:[1,0]
	v_pk_mul_f32 v[186:187], v[186:187], v[176:177] op_sel_hi:[1,0]
	v_pk_mul_f32 v[188:189], v[188:189], v[176:177] op_sel_hi:[1,0]
	ds_read_b128 v[154:157], v2 offset:43984
	s_waitcnt lgkmcnt(10)
	v_pk_fma_f32 v[182:183], v[192:193], v[212:213], v[182:183] op_sel_hi:[1,0,1]
	v_pk_fma_f32 v[184:185], v[194:195], v[212:213], v[184:185] op_sel_hi:[1,0,1]
	v_pk_fma_f32 v[186:187], v[196:197], v[212:213], v[186:187] op_sel_hi:[1,0,1]
	v_pk_fma_f32 v[188:189], v[198:199], v[212:213], v[188:189] op_sel_hi:[1,0,1]
	ds_read_b32 v210, v104 offset:44480
	ds_read_b128 v[126:129], v2 offset:43200
	s_waitcnt lgkmcnt(10)
	v_pk_fma_f32 v[96:97], v[96:97], v[166:167], v[182:183]
	v_pk_fma_f32 v[98:99], v[98:99], v[168:169], v[184:185]
	v_pk_fma_f32 v[100:101], v[100:101], v[170:171], v[186:187]
	v_pk_fma_f32 v[102:103], v[102:103], v[172:173], v[188:189]
	ds_read_b128 v[130:133], v2 offset:43216
	ds_read_b128 v[158:161], v2 offset:44224
	ds_read_b128 v[162:165], v2 offset:44240
	s_waitcnt lgkmcnt(9)
	v_pk_mul_f32 v[134:135], v[96:97], v[134:135]
	v_pk_mul_f32 v[200:201], v[96:97], v[200:201]
	v_pk_fma_f32 v[134:135], v[98:99], v[136:137], v[134:135]
	v_pk_fma_f32 v[200:201], v[98:99], v[202:203], v[200:201]
	v_pk_fma_f32 v[134:135], v[100:101], v[138:139], v[134:135]
	v_pk_fma_f32 v[200:201], v[100:101], v[204:205], v[200:201]
	v_pk_fma_f32 v[134:135], v[102:103], v[140:141], v[134:135]
	v_pk_fma_f32 v[200:201], v[102:103], v[206:207], v[200:201]
	v_add_f32_e32 v136, v134, v135
	v_add_f32_e32 v208, v200, v201
	ds_read_b128 v[174:177], v2 offset:44896
	v_add_f32_dpp v136, v136, v136 quad_perm:[1,0,3,2] row_mask:0xf bank_mask:0xf bound_ctrl:1
	ds_read_b128 v[178:181], v2 offset:44912
	ds_read_b128 v[182:185], v2 offset:45152
	v_add_f32_dpp v136, v136, v136 quad_perm:[2,3,0,1] row_mask:0xf bank_mask:0xf bound_ctrl:1
	ds_read_b128 v[186:189], v2 offset:45168
	ds_read_b128 v[192:195], v2 offset:45408
	v_add_f32_dpp v136, v136, v136 row_half_mirror row_mask:0xf bank_mask:0xf bound_ctrl:1
	s_waitcnt lgkmcnt(12)
	v_pk_mul_f32 v[142:143], v[142:143], v[136:137] op_sel_hi:[1,0]
	v_pk_mul_f32 v[144:145], v[144:145], v[136:137] op_sel_hi:[1,0]
	v_pk_mul_f32 v[146:147], v[146:147], v[136:137] op_sel_hi:[1,0]
	v_pk_mul_f32 v[148:149], v[148:149], v[136:137] op_sel_hi:[1,0]
	ds_read_b128 v[196:199], v2 offset:45424
	s_waitcnt lgkmcnt(10)
	v_pk_fma_f32 v[142:143], v[150:151], v[210:211], v[142:143] op_sel_hi:[1,0,1]
	v_pk_fma_f32 v[144:145], v[152:153], v[210:211], v[144:145] op_sel_hi:[1,0,1]
	v_pk_fma_f32 v[146:147], v[154:155], v[210:211], v[146:147] op_sel_hi:[1,0,1]
	v_pk_fma_f32 v[148:149], v[156:157], v[210:211], v[148:149] op_sel_hi:[1,0,1]
	ds_read_b32 v212, v104 offset:45920
	ds_read_b128 v[166:169], v2 offset:44640
	s_waitcnt lgkmcnt(10)
	v_pk_fma_f32 v[96:97], v[96:97], v[126:127], v[142:143]
	v_pk_fma_f32 v[98:99], v[98:99], v[128:129], v[144:145]
	v_pk_fma_f32 v[100:101], v[100:101], v[130:131], v[146:147]
	v_pk_fma_f32 v[102:103], v[102:103], v[132:133], v[148:149]
	ds_read_b128 v[170:173], v2 offset:44656
	ds_read_b128 v[200:203], v2 offset:45664
	ds_read_b128 v[204:207], v2 offset:45680
	s_waitcnt lgkmcnt(0)
	v_pk_mul_f32 v[174:175], v[96:97], v[174:175]
	v_pk_mul_f32 v[158:159], v[96:97], v[158:159]
	v_pk_fma_f32 v[174:175], v[98:99], v[176:177], v[174:175]
	v_pk_fma_f32 v[158:159], v[98:99], v[160:161], v[158:159]
	v_pk_fma_f32 v[174:175], v[100:101], v[178:179], v[174:175]
	v_pk_fma_f32 v[158:159], v[100:101], v[162:163], v[158:159]
	v_pk_fma_f32 v[174:175], v[102:103], v[180:181], v[174:175]
	v_pk_fma_f32 v[158:159], v[102:103], v[164:165], v[158:159]
	v_add_f32_e32 v176, v174, v175
	v_add_f32_e32 v191, v158, v159
	s_nop 0
	v_add_f32_dpp v176, v176, v176 quad_perm:[1,0,3,2] row_mask:0xf bank_mask:0xf bound_ctrl:1
	s_nop 1
	v_add_f32_dpp v176, v176, v176 quad_perm:[2,3,0,1] row_mask:0xf bank_mask:0xf bound_ctrl:1
	s_nop 1
	v_add_f32_dpp v176, v176, v176 row_half_mirror row_mask:0xf bank_mask:0xf bound_ctrl:1
	v_pk_mul_f32 v[182:183], v[182:183], v[176:177] op_sel_hi:[1,0]
	v_pk_mul_f32 v[184:185], v[184:185], v[176:177] op_sel_hi:[1,0]
	v_pk_mul_f32 v[186:187], v[186:187], v[176:177] op_sel_hi:[1,0]
	v_pk_mul_f32 v[188:189], v[188:189], v[176:177] op_sel_hi:[1,0]
	v_pk_fma_f32 v[182:183], v[192:193], v[212:213], v[182:183] op_sel_hi:[1,0,1]
	v_pk_fma_f32 v[184:185], v[194:195], v[212:213], v[184:185] op_sel_hi:[1,0,1]
	v_pk_fma_f32 v[186:187], v[196:197], v[212:213], v[186:187] op_sel_hi:[1,0,1]
	v_pk_fma_f32 v[188:189], v[198:199], v[212:213], v[188:189] op_sel_hi:[1,0,1]
	v_pk_fma_f32 v[96:97], v[96:97], v[166:167], v[182:183]
	v_pk_fma_f32 v[98:99], v[98:99], v[168:169], v[184:185]
	v_pk_fma_f32 v[100:101], v[100:101], v[170:171], v[186:187]
	v_pk_fma_f32 v[102:103], v[102:103], v[172:173], v[188:189]
	v_pk_mul_f32 v[200:201], v[96:97], v[200:201]
	s_nop 0
	v_pk_fma_f32 v[200:201], v[98:99], v[202:203], v[200:201]
	s_nop 0
	v_pk_fma_f32 v[200:201], v[100:101], v[204:205], v[200:201]
	s_nop 0
	v_pk_fma_f32 v[200:201], v[102:103], v[206:207], v[200:201]
	s_nop 0
	v_add_f32_e32 v59, v200, v201
	v_cndmask_b32_e64 v200, v213, v211, s[10:11]
	v_cndmask_b32_e64 v204, v211, v213, s[10:11]
	v_cndmask_b32_e64 v201, v215, v214, s[10:11]
	v_cndmask_b32_e64 v205, v214, v215, s[10:11]
	v_cndmask_b32_e64 v202, v208, v216, s[10:11]
	v_cndmask_b32_e64 v206, v216, v208, s[10:11]
	v_cndmask_b32_e64 v203, v59, v191, s[10:11]
	v_cndmask_b32_e64 v207, v191, v59, s[10:11]
	v_add_f32_dpp v200, v204, v200 quad_perm:[1,0,3,2] row_mask:0xf bank_mask:0xf bound_ctrl:1
	v_add_f32_dpp v201, v205, v201 quad_perm:[1,0,3,2] row_mask:0xf bank_mask:0xf bound_ctrl:1
	v_add_f32_dpp v202, v206, v202 quad_perm:[1,0,3,2] row_mask:0xf bank_mask:0xf bound_ctrl:1
	v_add_f32_dpp v203, v207, v203 quad_perm:[1,0,3,2] row_mask:0xf bank_mask:0xf bound_ctrl:1
	v_cndmask_b32_e64 v204, v201, v200, s[12:13]
	v_cndmask_b32_e64 v206, v200, v201, s[12:13]
	v_cndmask_b32_e64 v205, v203, v202, s[12:13]
	v_cndmask_b32_e64 v207, v202, v203, s[12:13]
	v_add_f32_dpp v204, v206, v204 quad_perm:[2,3,0,1] row_mask:0xf bank_mask:0xf bound_ctrl:1
	s_nop 0
	v_add_f32_dpp v205, v207, v205 quad_perm:[2,3,0,1] row_mask:0xf bank_mask:0xf bound_ctrl:1
	v_xor_b32_e32 v202, 4, v121
	v_cndmask_b32_e64 v200, v205, v204, s[14:15]
	v_cndmask_b32_e64 v201, v204, v205, s[14:15]
	v_lshlrev_b32_e32 v202, 2, v202
	ds_bpermute_b32 v201, v202, v201
	s_waitcnt lgkmcnt(0)
	v_add_f32_e32 v200, v200, v201
	ds_write_b32 v105, v200 offset:3072
	s_setprio 0
